# P5a conv prologue de-serialised: the first two rows' loads are issued with the conv weights and halo rows, one wait instead of two
# baseline (speedup 1.0000x reference)
; __device__ __forceinline__ u32x4 pack8(const f32x4 a, const f32x4 b) { u32x4 w; w.x = cvt_pk_bf16(a[0], a[1]); w.y = cvt_pk_bf16(a[2], a[3]); w.z = cvt_pk_bf16(b[0], b[1]); w.w = cvt_pk_bf16(b[2], b[3]); return w; }
; __device__ __forceinline__ void p5_conv(const Args& A, int lane, int wave, bf16_t* Gout) {
;     ...
;         if ((r0 & (SEQ - 1)) != 0) { pg8::unpack8(*(const u32x4*)(CU + (size_t)(r0 - 2) * DM + c0), p2a, p2b); pg8::unpack8(*(const u32x4*)(CU + (size_t)(r0 - 1) * DM + c0), p1a, p1b); }
;         u32x4 cq[4], bq[4];
; #pragma unroll
;         for (int i = 0; i < 4; ++i) { const size_t off = (size_t)(r0 + i) * DM + c0; cq[i] = *(const u32x4*)(CU + off); bq[i] = *(const u32x4*)(BG + off); }
; #pragma unroll
;         for (int t = 0; t < 32; ++t) { const size_t off = (size_t)(r0 + t) * DM + c0;
;             f32x4 ca, cb, ba, bb; pg8::unpack8(cq[t & 3], ca, cb); pg8::unpack8(bq[t & 3], ba, bb);
;             if (t + 4 < 32) { const size_t offn = (size_t)(r0 + t + 4) * DM + c0; cq[t & 3] = *(const u32x4*)(CU + offn); bq[t & 3] = *(const u32x4*)(BG + offn); }
;             const f32x4 oa = ba * ((w0a * p2a + w1a * p1a) + w2a * ca), ob = bb * ((w0b * p2b + w1b * p1b) + w2b * cb);
;             *(u32x4*)(Gout + off) = pg8::pack8(oa, ob);
;             p2a = p1a; p2b = p1b; p1a = ca; p1b = cb; }
.LBB0_631:
	s_ashr_i32 s15, s14, 31
	s_lshl_b64 s[18:19], s[14:15], 11
	s_or_b32 s16, s14, 1
	s_ashr_i32 s17, s16, 31
	s_lshl_b64 s[20:21], s[16:17], 11
	s_or_b32 s16, s14, 2
	s_or_b32 s24, s14, 3
	s_or_b32 s34, s14, 4
	s_ashr_i32 s17, s16, 31
	s_waitcnt vmcnt(0)
	v_pk_mul_f32 v[56:57], v[22:23], v[34:35]
	s_ashr_i32 s25, s24, 31
	s_ashr_i32 s35, s34, 31
	s_lshl_b64 s[22:23], s[16:17], 11
	v_pk_mul_f32 v[54:55], v[24:25], v[36:37]
	v_pk_fma_f32 v[86:87], v[18:19], v[38:39], v[56:57]
	s_lshl_b64 s[24:25], s[24:25], 11
	s_lshl_b64 s[16:17], s[34:35], 11
	v_or_b32_e32 v38, s22, v74
	v_mov_b32_e32 v39, s23
	v_pk_mul_f32 v[62:63], v[10:11], v[30:31]
	v_pk_mul_f32 v[64:65], v[12:13], v[32:33]
	v_pk_fma_f32 v[84:85], v[20:21], v[40:41], v[54:55]
	v_or_b32_e32 v40, s24, v74
	v_mov_b32_e32 v41, s25
	v_or_b32_e32 v54, s16, v74
	v_mov_b32_e32 v55, s17
	v_lshl_add_u64 v[56:57], s[6:7], 0, v[38:39]
	v_pk_fma_f32 v[28:29], v[8:9], v[28:29], v[64:65]
	v_pk_fma_f32 v[26:27], v[6:7], v[26:27], v[62:63]
	v_lshl_add_u64 v[90:91], s[4:5], 0, v[38:39]
	v_lshl_add_u64 v[92:93], s[6:7], 0, v[40:41]
	v_lshl_add_u64 v[94:95], s[4:5], 0, v[40:41]
	v_lshl_add_u64 v[96:97], s[4:5], 0, v[54:55]
	v_lshl_add_u64 v[98:99], s[6:7], 0, v[54:55]
	global_load_dwordx4 v[62:65], v[56:57], off
	global_load_dwordx4 v[66:69], v[90:91], off
	global_load_dwordx4 v[70:73], v[92:93], off
	global_load_dwordx4 v[80:83], v[94:95], off
	s_nop 0
	global_load_dwordx4 v[54:57], v[98:99], off
	global_load_dwordx4 v[38:41], v[96:97], off
	v_lshl_add_u64 v[76:77], s[0:1], 0, v[74:75]
	v_lshl_add_u64 v[88:89], v[76:77], 0, s[18:19]
	s_or_b32 s18, s14, 5
	s_ashr_i32 s19, s18, 31
	s_lshl_b64 s[18:19], s[18:19], 11
	v_lshlrev_b32_e32 v90, 16, v42
	v_and_b32_e32 v91, 0xffff0000, v42
	v_lshlrev_b32_e32 v92, 16, v43
	v_and_b32_e32 v93, 0xffff0000, v43
	v_lshlrev_b32_e32 v94, 16, v44
	v_and_b32_e32 v95, 0xffff0000, v44
	v_lshlrev_b32_e32 v96, 16, v45
	v_and_b32_e32 v97, 0xffff0000, v45
	v_lshlrev_b32_e32 v42, 16, v46
	v_and_b32_e32 v43, 0xffff0000, v46
	v_lshlrev_b32_e32 v44, 16, v47
	v_and_b32_e32 v45, 0xffff0000, v47
	v_lshlrev_b32_e32 v46, 16, v48
	v_and_b32_e32 v47, 0xffff0000, v48
	v_lshlrev_b32_e32 v48, 16, v49
	v_and_b32_e32 v49, 0xffff0000, v49
	v_pk_fma_f32 v[86:87], v[14:15], v[90:91], v[86:87]
	v_pk_fma_f32 v[84:85], v[16:17], v[92:93], v[84:85]
	v_pk_fma_f32 v[26:27], v[2:3], v[94:95], v[26:27]
	v_pk_fma_f32 v[28:29], v[4:5], v[96:97], v[28:29]
	v_pk_mul_f32 v[44:45], v[84:85], v[44:45]
	v_pk_mul_f32 v[42:43], v[86:87], v[42:43]
	v_pk_mul_f32 v[48:49], v[28:29], v[48:49]
	v_pk_mul_f32 v[28:29], v[26:27], v[46:47]
	v_cvt_pk_bf16_f32 v26, v42, v43
	v_cvt_pk_bf16_f32 v27, v44, v45
	v_lshlrev_b32_e32 v98, 16, v50
	v_cvt_pk_bf16_f32 v28, v28, v29
	v_cvt_pk_bf16_f32 v29, v48, v49
	global_store_dwordx4 v[88:89], v[26:29], off
	v_and_b32_e32 v99, 0xffff0000, v50
	v_lshlrev_b32_e32 v100, 16, v51
	v_or_b32_e32 v26, s18, v74
	v_mov_b32_e32 v27, s19
	v_lshl_add_u64 v[28:29], s[4:5], 0, v[26:27]
	v_lshl_add_u64 v[26:27], s[6:7], 0, v[26:27]
	v_and_b32_e32 v101, 0xffff0000, v51
	v_lshlrev_b32_e32 v102, 16, v52
	v_and_b32_e32 v103, 0xffff0000, v52
	v_lshlrev_b32_e32 v84, 16, v53
	v_and_b32_e32 v85, 0xffff0000, v53
	v_lshlrev_b32_e32 v46, 16, v58
	v_and_b32_e32 v47, 0xffff0000, v58
	v_lshlrev_b32_e32 v48, 16, v59
	v_and_b32_e32 v49, 0xffff0000, v59
	v_lshlrev_b32_e32 v50, 16, v60
	v_and_b32_e32 v51, 0xffff0000, v60
	v_lshlrev_b32_e32 v52, 16, v61
	v_and_b32_e32 v53, 0xffff0000, v61
	global_load_dwordx4 v[42:45], v[26:27], off
	s_nop 0
	global_load_dwordx4 v[26:29], v[28:29], off
	v_pk_mul_f32 v[58:59], v[22:23], v[90:91]
	v_pk_mul_f32 v[60:61], v[24:25], v[92:93]
	v_pk_fma_f32 v[34:35], v[18:19], v[34:35], v[58:59]
	v_pk_fma_f32 v[36:37], v[20:21], v[36:37], v[60:61]
	v_pk_fma_f32 v[34:35], v[14:15], v[98:99], v[34:35]
	v_pk_fma_f32 v[36:37], v[16:17], v[100:101], v[36:37]
	v_pk_mul_f32 v[34:35], v[34:35], v[46:47]
	v_pk_mul_f32 v[36:37], v[36:37], v[48:49]
	v_pk_mul_f32 v[46:47], v[10:11], v[94:95]
	v_pk_mul_f32 v[48:49], v[12:13], v[96:97]
	v_pk_fma_f32 v[30:31], v[6:7], v[30:31], v[46:47]
	v_pk_fma_f32 v[32:33], v[8:9], v[32:33], v[48:49]
	v_pk_fma_f32 v[30:31], v[2:3], v[102:103], v[30:31]
	v_pk_fma_f32 v[32:33], v[4:5], v[84:85], v[32:33]
	v_pk_mul_f32 v[58:59], v[22:23], v[98:99]
	v_pk_mul_f32 v[46:47], v[32:33], v[52:53]
	v_pk_mul_f32 v[32:33], v[30:31], v[50:51]
	v_cvt_pk_bf16_f32 v30, v34, v35
	v_lshl_add_u64 v[34:35], v[76:77], 0, s[20:21]
	s_or_b32 s20, s14, 6
	s_ashr_i32 s21, s20, 31
	v_cvt_pk_bf16_f32 v31, v36, v37
	s_lshl_b64 s[20:21], s[20:21], 11
	v_cvt_pk_bf16_f32 v32, v32, v33
	v_cvt_pk_bf16_f32 v33, v46, v47
	global_store_dwordx4 v[34:35], v[30:33], off
	s_waitcnt vmcnt(9)
	v_lshlrev_b32_e32 v86, 16, v62
	v_and_b32_e32 v87, 0xffff0000, v62
	v_or_b32_e32 v30, s20, v74
	v_mov_b32_e32 v31, s21
	v_lshl_add_u64 v[32:33], s[4:5], 0, v[30:31]
	v_lshl_add_u64 v[30:31], s[6:7], 0, v[30:31]
	global_load_dwordx4 v[46:49], v[30:31], off
	s_nop 0
	global_load_dwordx4 v[30:33], v[32:33], off
	v_pk_fma_f32 v[58:59], v[18:19], v[90:91], v[58:59]
	s_waitcnt vmcnt(10)
; __device__ __forceinline__ u32x4 pack8(const f32x4 a, const f32x4 b) { u32x4 w; w.x = cvt_pk_bf16(a[0], a[1]); w.y = cvt_pk_bf16(a[2], a[3]); w.z = cvt_pk_bf16(b[0], b[1]); w.w = cvt_pk_bf16(b[2], b[3]); return w; }
; __device__ __forceinline__ void p5_conv(const Args& A, int lane, int wave, bf16_t* Gout) {
;     ...
;         for (int t = 0; t < 32; ++t) { const size_t off = (size_t)(r0 + t) * DM + c0;
;             f32x4 ca, cb, ba, bb; pg8::unpack8(cq[t & 3], ca, cb); pg8::unpack8(bq[t & 3], ba, bb);
;             if (t + 4 < 32) { const size_t offn = (size_t)(r0 + t + 4) * DM + c0; cq[t & 3] = *(const u32x4*)(CU + offn); bq[t & 3] = *(const u32x4*)(BG + offn); }
;             const f32x4 oa = ba * ((w0a * p2a + w1a * p1a) + w2a * ca), ob = bb * ((w0b * p2b + w1b * p1b) + w2b * cb);
;             *(u32x4*)(Gout + off) = pg8::pack8(oa, ob);
;             p2a = p1a; p2b = p1b; p1a = ca; p1b = cb; }
	v_lshlrev_b32_e32 v34, 16, v66
	v_and_b32_e32 v35, 0xffff0000, v66
	v_pk_fma_f32 v[58:59], v[14:15], v[86:87], v[58:59]
	v_pk_mul_f32 v[60:61], v[24:25], v[100:101]
	v_pk_mul_f32 v[34:35], v[58:59], v[34:35]
	v_pk_mul_f32 v[58:59], v[10:11], v[102:103]
	v_lshlrev_b32_e32 v62, 16, v63
	v_and_b32_e32 v63, 0xffff0000, v63
	v_lshlrev_b32_e32 v88, 16, v64
	v_and_b32_e32 v89, 0xffff0000, v64
	v_pk_fma_f32 v[60:61], v[20:21], v[92:93], v[60:61]
	v_pk_fma_f32 v[58:59], v[6:7], v[94:95], v[58:59]
	v_lshlrev_b32_e32 v36, 16, v67
	v_and_b32_e32 v37, 0xffff0000, v67
	v_lshlrev_b32_e32 v50, 16, v68
	v_and_b32_e32 v51, 0xffff0000, v68
	v_pk_fma_f32 v[60:61], v[16:17], v[62:63], v[60:61]
	v_pk_fma_f32 v[58:59], v[2:3], v[88:89], v[58:59]
	v_pk_mul_f32 v[36:37], v[60:61], v[36:37]
	v_pk_mul_f32 v[50:51], v[58:59], v[50:51]
	v_pk_mul_f32 v[60:61], v[12:13], v[84:85]
	v_cvt_pk_bf16_f32 v34, v34, v35
	v_cvt_pk_bf16_f32 v35, v36, v37
	v_cvt_pk_bf16_f32 v36, v50, v51
	v_lshl_add_u64 v[50:51], v[76:77], 0, s[22:23]
	s_or_b32 s22, s14, 7
	v_lshlrev_b32_e32 v64, 16, v65
	v_and_b32_e32 v65, 0xffff0000, v65
	v_pk_fma_f32 v[60:61], v[8:9], v[96:97], v[60:61]
	s_ashr_i32 s23, s22, 31
	v_lshlrev_b32_e32 v52, 16, v69
	v_and_b32_e32 v53, 0xffff0000, v69
	v_pk_fma_f32 v[60:61], v[4:5], v[64:65], v[60:61]
	s_lshl_b64 s[22:23], s[22:23], 11
	v_pk_mul_f32 v[52:53], v[60:61], v[52:53]
	v_pk_mul_f32 v[90:91], v[22:23], v[86:87]
	v_cvt_pk_bf16_f32 v37, v52, v53
	global_store_dwordx4 v[50:51], v[34:37], off
	s_waitcnt vmcnt(10)
	v_lshlrev_b32_e32 v66, 16, v70
	v_and_b32_e32 v67, 0xffff0000, v70
	v_or_b32_e32 v34, s22, v74
	v_mov_b32_e32 v35, s23
	v_lshl_add_u64 v[36:37], s[4:5], 0, v[34:35]
	v_lshl_add_u64 v[34:35], s[6:7], 0, v[34:35]
	global_load_dwordx4 v[50:53], v[34:35], off
	s_nop 0
	global_load_dwordx4 v[34:37], v[36:37], off
	v_pk_fma_f32 v[90:91], v[18:19], v[98:99], v[90:91]
	s_waitcnt vmcnt(11)
	v_lshlrev_b32_e32 v58, 16, v80
	v_and_b32_e32 v59, 0xffff0000, v80
	v_pk_fma_f32 v[90:91], v[14:15], v[66:67], v[90:91]
	v_pk_mul_f32 v[92:93], v[24:25], v[62:63]
	v_pk_mul_f32 v[58:59], v[90:91], v[58:59]
	v_pk_mul_f32 v[90:91], v[10:11], v[88:89]
	v_lshlrev_b32_e32 v68, 16, v71
	v_and_b32_e32 v69, 0xffff0000, v71
	v_lshlrev_b32_e32 v70, 16, v72
	v_and_b32_e32 v71, 0xffff0000, v72
	v_pk_fma_f32 v[92:93], v[20:21], v[100:101], v[92:93]
	v_pk_fma_f32 v[90:91], v[6:7], v[102:103], v[90:91]
	v_lshlrev_b32_e32 v60, 16, v81
	v_and_b32_e32 v61, 0xffff0000, v81
	v_lshlrev_b32_e32 v80, 16, v82
	v_and_b32_e32 v81, 0xffff0000, v82
	v_pk_fma_f32 v[92:93], v[16:17], v[68:69], v[92:93]
	v_pk_fma_f32 v[90:91], v[2:3], v[70:71], v[90:91]
	v_pk_mul_f32 v[60:61], v[92:93], v[60:61]
	v_pk_mul_f32 v[92:93], v[12:13], v[64:65]
	v_pk_mul_f32 v[80:81], v[90:91], v[80:81]
	v_lshlrev_b32_e32 v72, 16, v73
	v_and_b32_e32 v73, 0xffff0000, v73
	v_pk_fma_f32 v[84:85], v[8:9], v[84:85], v[92:93]
	v_cvt_pk_bf16_f32 v58, v58, v59
	v_cvt_pk_bf16_f32 v59, v60, v61
	v_cvt_pk_bf16_f32 v60, v80, v81
	v_lshl_add_u64 v[80:81], v[76:77], 0, s[24:25]
	s_or_b32 s24, s14, 8
	v_lshlrev_b32_e32 v82, 16, v83
	v_and_b32_e32 v83, 0xffff0000, v83
	v_pk_fma_f32 v[84:85], v[4:5], v[72:73], v[84:85]
	s_ashr_i32 s25, s24, 31
	v_pk_mul_f32 v[82:83], v[84:85], v[82:83]
	s_lshl_b64 s[24:25], s[24:25], 11
	v_cvt_pk_bf16_f32 v61, v82, v83
	v_pk_mul_f32 v[98:99], v[24:25], v[68:69]
	global_store_dwordx4 v[80:81], v[58:61], off
	s_waitcnt vmcnt(11)
	v_lshlrev_b32_e32 v82, 16, v55
	v_and_b32_e32 v83, 0xffff0000, v55
	s_waitcnt vmcnt(10)
	v_lshlrev_b32_e32 v58, 16, v38
	v_and_b32_e32 v59, 0xffff0000, v38
	v_lshlrev_b32_e32 v60, 16, v39
	v_and_b32_e32 v61, 0xffff0000, v39
	v_or_b32_e32 v38, s24, v74
	v_mov_b32_e32 v39, s25
	v_pk_fma_f32 v[62:63], v[20:21], v[62:63], v[98:99]
	v_lshlrev_b32_e32 v92, 16, v40
	v_and_b32_e32 v93, 0xffff0000, v40
	v_lshlrev_b32_e32 v94, 16, v41
	v_and_b32_e32 v95, 0xffff0000, v41
	v_lshl_add_u64 v[40:41], s[4:5], 0, v[38:39]
	v_lshl_add_u64 v[38:39], s[6:7], 0, v[38:39]
	v_pk_fma_f32 v[62:63], v[16:17], v[82:83], v[62:63]
	v_lshlrev_b32_e32 v80, 16, v54
	v_and_b32_e32 v81, 0xffff0000, v54
	v_lshlrev_b32_e32 v84, 16, v56
	v_and_b32_e32 v85, 0xffff0000, v56
	v_lshlrev_b32_e32 v90, 16, v57
	v_and_b32_e32 v91, 0xffff0000, v57
	global_load_dwordx4 v[54:57], v[38:39], off
	s_nop 0
	global_load_dwordx4 v[38:41], v[40:41], off
	v_pk_mul_f32 v[96:97], v[22:23], v[66:67]
	v_pk_mul_f32 v[60:61], v[62:63], v[60:61]
	v_pk_mul_f32 v[62:63], v[10:11], v[70:71]
	v_pk_fma_f32 v[86:87], v[18:19], v[86:87], v[96:97]
	v_pk_fma_f32 v[62:63], v[6:7], v[88:89], v[62:63]
	v_pk_fma_f32 v[86:87], v[14:15], v[80:81], v[86:87]
	v_pk_fma_f32 v[62:63], v[2:3], v[84:85], v[62:63]
	v_pk_mul_f32 v[58:59], v[86:87], v[58:59]
	v_pk_mul_f32 v[86:87], v[12:13], v[72:73]
	v_pk_mul_f32 v[62:63], v[62:63], v[92:93]
	v_pk_fma_f32 v[64:65], v[8:9], v[64:65], v[86:87]
	v_cvt_pk_bf16_f32 v58, v58, v59
	v_cvt_pk_bf16_f32 v59, v60, v61
	v_cvt_pk_bf16_f32 v60, v62, v63
	v_lshl_add_u64 v[62:63], v[76:77], 0, s[16:17]
	s_or_b32 s16, s14, 9
	v_pk_fma_f32 v[64:65], v[4:5], v[90:91], v[64:65]
	s_ashr_i32 s17, s16, 31
	v_pk_mul_f32 v[64:65], v[64:65], v[94:95]
	s_lshl_b64 s[16:17], s[16:17], 11
	v_cvt_pk_bf16_f32 v61, v64, v65
	global_store_dwordx4 v[62:63], v[58:61], off
	s_waitcnt vmcnt(10)
; __device__ __forceinline__ u32x4 pack8(const f32x4 a, const f32x4 b) { u32x4 w; w.x = cvt_pk_bf16(a[0], a[1]); w.y = cvt_pk_bf16(a[2], a[3]); w.z = cvt_pk_bf16(b[0], b[1]); w.w = cvt_pk_bf16(b[2], b[3]); return w; }
; __device__ __forceinline__ void p5_conv(const Args& A, int lane, int wave, bf16_t* Gout) {
;     ...
;         for (int t = 0; t < 32; ++t) { const size_t off = (size_t)(r0 + t) * DM + c0;
;             f32x4 ca, cb, ba, bb; pg8::unpack8(cq[t & 3], ca, cb); pg8::unpack8(bq[t & 3], ba, bb);
;             if (t + 4 < 32) { const size_t offn = (size_t)(r0 + t + 4) * DM + c0; cq[t & 3] = *(const u32x4*)(CU + offn); bq[t & 3] = *(const u32x4*)(BG + offn); }
;             const f32x4 oa = ba * ((w0a * p2a + w1a * p1a) + w2a * ca), ob = bb * ((w0b * p2b + w1b * p1b) + w2b * cb);
;             *(u32x4*)(Gout + off) = pg8::pack8(oa, ob);
;             p2a = p1a; p2b = p1b; p1a = ca; p1b = cb; }
	v_lshlrev_b32_e32 v92, 16, v28
	v_and_b32_e32 v93, 0xffff0000, v28
	v_lshlrev_b32_e32 v58, 16, v26
	v_and_b32_e32 v59, 0xffff0000, v26
	v_lshlrev_b32_e32 v60, 16, v27
	v_and_b32_e32 v61, 0xffff0000, v27
	v_or_b32_e32 v26, s16, v74
	v_mov_b32_e32 v27, s17
	v_lshlrev_b32_e32 v94, 16, v29
	v_and_b32_e32 v95, 0xffff0000, v29
	v_lshl_add_u64 v[28:29], s[4:5], 0, v[26:27]
	v_lshl_add_u64 v[26:27], s[6:7], 0, v[26:27]
	v_pk_mul_f32 v[96:97], v[22:23], v[80:81]
	v_lshlrev_b32_e32 v62, 16, v42
	v_and_b32_e32 v63, 0xffff0000, v42
	v_lshlrev_b32_e32 v64, 16, v43
	v_and_b32_e32 v65, 0xffff0000, v43
	v_lshlrev_b32_e32 v86, 16, v44
	v_and_b32_e32 v87, 0xffff0000, v44
	v_lshlrev_b32_e32 v88, 16, v45
	v_and_b32_e32 v89, 0xffff0000, v45
	global_load_dwordx4 v[42:45], v[26:27], off
	s_nop 0
	global_load_dwordx4 v[26:29], v[28:29], off
	v_pk_fma_f32 v[66:67], v[18:19], v[66:67], v[96:97]
	v_pk_mul_f32 v[98:99], v[24:25], v[82:83]
	v_pk_fma_f32 v[66:67], v[14:15], v[62:63], v[66:67]
	v_pk_fma_f32 v[68:69], v[20:21], v[68:69], v[98:99]
	v_pk_mul_f32 v[58:59], v[66:67], v[58:59]
	v_pk_mul_f32 v[66:67], v[10:11], v[84:85]
	v_pk_fma_f32 v[68:69], v[16:17], v[64:65], v[68:69]
	v_pk_fma_f32 v[66:67], v[6:7], v[70:71], v[66:67]
	v_pk_mul_f32 v[60:61], v[68:69], v[60:61]
	v_pk_fma_f32 v[66:67], v[2:3], v[86:87], v[66:67]
	v_pk_mul_f32 v[68:69], v[12:13], v[90:91]
	v_pk_mul_f32 v[66:67], v[66:67], v[92:93]
	v_pk_fma_f32 v[68:69], v[8:9], v[72:73], v[68:69]
	v_cvt_pk_bf16_f32 v58, v58, v59
	v_cvt_pk_bf16_f32 v59, v60, v61
	v_cvt_pk_bf16_f32 v60, v66, v67
	v_lshl_add_u64 v[66:67], v[76:77], 0, s[18:19]
	s_or_b32 s18, s14, 10
	v_pk_fma_f32 v[68:69], v[4:5], v[88:89], v[68:69]
	s_ashr_i32 s19, s18, 31
	v_pk_mul_f32 v[68:69], v[68:69], v[94:95]
	s_lshl_b64 s[18:19], s[18:19], 11
	v_cvt_pk_bf16_f32 v61, v68, v69
	global_store_dwordx4 v[66:67], v[58:61], off
	s_waitcnt vmcnt(10)
	v_lshlrev_b32_e32 v92, 16, v32
	v_and_b32_e32 v93, 0xffff0000, v32
	v_lshlrev_b32_e32 v58, 16, v30
	v_and_b32_e32 v59, 0xffff0000, v30
	v_lshlrev_b32_e32 v60, 16, v31
	v_and_b32_e32 v61, 0xffff0000, v31
	v_or_b32_e32 v30, s18, v74
	v_mov_b32_e32 v31, s19
	v_lshlrev_b32_e32 v94, 16, v33
	v_and_b32_e32 v95, 0xffff0000, v33
	v_lshl_add_u64 v[32:33], s[4:5], 0, v[30:31]
	v_lshl_add_u64 v[30:31], s[6:7], 0, v[30:31]
	v_lshlrev_b32_e32 v66, 16, v46
	v_and_b32_e32 v67, 0xffff0000, v46
	v_lshlrev_b32_e32 v68, 16, v47
	v_and_b32_e32 v69, 0xffff0000, v47
	v_lshlrev_b32_e32 v70, 16, v48
	v_and_b32_e32 v71, 0xffff0000, v48
	v_lshlrev_b32_e32 v72, 16, v49
	v_and_b32_e32 v73, 0xffff0000, v49
	global_load_dwordx4 v[46:49], v[30:31], off
	s_nop 0
	global_load_dwordx4 v[30:33], v[32:33], off
	v_pk_mul_f32 v[96:97], v[22:23], v[62:63]
	v_pk_mul_f32 v[98:99], v[24:25], v[64:65]
	v_pk_fma_f32 v[80:81], v[18:19], v[80:81], v[96:97]
	v_pk_fma_f32 v[82:83], v[20:21], v[82:83], v[98:99]
	v_pk_fma_f32 v[80:81], v[14:15], v[66:67], v[80:81]
	v_pk_fma_f32 v[82:83], v[16:17], v[68:69], v[82:83]
	v_pk_mul_f32 v[58:59], v[80:81], v[58:59]
	v_pk_mul_f32 v[80:81], v[10:11], v[86:87]
	v_pk_mul_f32 v[60:61], v[82:83], v[60:61]
	v_pk_fma_f32 v[80:81], v[6:7], v[84:85], v[80:81]
	v_pk_mul_f32 v[82:83], v[12:13], v[88:89]
	v_pk_fma_f32 v[80:81], v[2:3], v[70:71], v[80:81]
	v_pk_fma_f32 v[82:83], v[8:9], v[90:91], v[82:83]
	v_pk_mul_f32 v[80:81], v[80:81], v[92:93]
	v_cvt_pk_bf16_f32 v58, v58, v59
	v_cvt_pk_bf16_f32 v59, v60, v61
	v_pk_fma_f32 v[82:83], v[4:5], v[72:73], v[82:83]
	v_cvt_pk_bf16_f32 v60, v80, v81
	v_lshl_add_u64 v[80:81], v[76:77], 0, s[20:21]
	s_or_b32 s20, s14, 11
	s_ashr_i32 s21, s20, 31
	v_pk_mul_f32 v[82:83], v[82:83], v[94:95]
	s_lshl_b64 s[20:21], s[20:21], 11
	v_cvt_pk_bf16_f32 v61, v82, v83
	global_store_dwordx4 v[80:81], v[58:61], off
	s_waitcnt vmcnt(10)
	v_lshlrev_b32_e32 v92, 16, v36
	v_and_b32_e32 v93, 0xffff0000, v36
	v_lshlrev_b32_e32 v58, 16, v34
	v_and_b32_e32 v59, 0xffff0000, v34
	v_lshlrev_b32_e32 v60, 16, v35
	v_and_b32_e32 v61, 0xffff0000, v35
	v_or_b32_e32 v34, s20, v74
	v_mov_b32_e32 v35, s21
	v_lshlrev_b32_e32 v94, 16, v37
	v_and_b32_e32 v95, 0xffff0000, v37
	v_lshl_add_u64 v[36:37], s[4:5], 0, v[34:35]
	v_lshl_add_u64 v[34:35], s[6:7], 0, v[34:35]
	v_lshlrev_b32_e32 v80, 16, v50
	v_and_b32_e32 v81, 0xffff0000, v50
	v_lshlrev_b32_e32 v82, 16, v51
	v_and_b32_e32 v83, 0xffff0000, v51
	v_lshlrev_b32_e32 v84, 16, v52
	v_and_b32_e32 v85, 0xffff0000, v52
	v_lshlrev_b32_e32 v90, 16, v53
	v_and_b32_e32 v91, 0xffff0000, v53
	global_load_dwordx4 v[50:53], v[34:35], off
	s_nop 0
	global_load_dwordx4 v[34:37], v[36:37], off
	v_pk_mul_f32 v[96:97], v[22:23], v[66:67]
	v_pk_mul_f32 v[98:99], v[24:25], v[68:69]
	v_pk_fma_f32 v[62:63], v[18:19], v[62:63], v[96:97]
	v_pk_fma_f32 v[64:65], v[20:21], v[64:65], v[98:99]
	v_pk_fma_f32 v[62:63], v[14:15], v[80:81], v[62:63]
	v_pk_fma_f32 v[64:65], v[16:17], v[82:83], v[64:65]
	v_pk_mul_f32 v[58:59], v[62:63], v[58:59]
	v_pk_mul_f32 v[62:63], v[10:11], v[70:71]
	v_pk_mul_f32 v[60:61], v[64:65], v[60:61]
	v_pk_fma_f32 v[62:63], v[6:7], v[86:87], v[62:63]
	v_pk_mul_f32 v[64:65], v[12:13], v[72:73]
	v_pk_fma_f32 v[62:63], v[2:3], v[84:85], v[62:63]
	v_pk_fma_f32 v[64:65], v[8:9], v[88:89], v[64:65]
	v_pk_mul_f32 v[62:63], v[62:63], v[92:93]
	v_cvt_pk_bf16_f32 v58, v58, v59
	v_cvt_pk_bf16_f32 v59, v60, v61
	v_pk_fma_f32 v[64:65], v[4:5], v[90:91], v[64:65]
	v_cvt_pk_bf16_f32 v60, v62, v63
	v_lshl_add_u64 v[62:63], v[76:77], 0, s[22:23]
	s_or_b32 s22, s14, 12
	s_ashr_i32 s23, s22, 31
	v_pk_mul_f32 v[64:65], v[64:65], v[94:95]
	s_lshl_b64 s[22:23], s[22:23], 11
	v_cvt_pk_bf16_f32 v61, v64, v65
	v_pk_mul_f32 v[96:97], v[22:23], v[80:81]
	global_store_dwordx4 v[62:63], v[58:61], off
	s_waitcnt vmcnt(11)
; __device__ __forceinline__ u32x4 pack8(const f32x4 a, const f32x4 b) { u32x4 w; w.x = cvt_pk_bf16(a[0], a[1]); w.y = cvt_pk_bf16(a[2], a[3]); w.z = cvt_pk_bf16(b[0], b[1]); w.w = cvt_pk_bf16(b[2], b[3]); return w; }
; __device__ __forceinline__ void p5_conv(const Args& A, int lane, int wave, bf16_t* Gout) {
;     ...
;         for (int t = 0; t < 32; ++t) { const size_t off = (size_t)(r0 + t) * DM + c0;
;             f32x4 ca, cb, ba, bb; pg8::unpack8(cq[t & 3], ca, cb); pg8::unpack8(bq[t & 3], ba, bb);
;             if (t + 4 < 32) { const size_t offn = (size_t)(r0 + t + 4) * DM + c0; cq[t & 3] = *(const u32x4*)(CU + offn); bq[t & 3] = *(const u32x4*)(BG + offn); }
;             const f32x4 oa = ba * ((w0a * p2a + w1a * p1a) + w2a * ca), ob = bb * ((w0b * p2b + w1b * p1b) + w2b * cb);
;             *(u32x4*)(Gout + off) = pg8::pack8(oa, ob);
;             p2a = p1a; p2b = p1b; p1a = ca; p1b = cb; }
	v_lshlrev_b32_e32 v62, 16, v54
	v_and_b32_e32 v63, 0xffff0000, v54
	s_waitcnt vmcnt(10)
	v_lshlrev_b32_e32 v58, 16, v38
	v_and_b32_e32 v59, 0xffff0000, v38
	v_lshlrev_b32_e32 v60, 16, v39
	v_and_b32_e32 v61, 0xffff0000, v39
	v_or_b32_e32 v38, s22, v74
	v_mov_b32_e32 v39, s23
	v_pk_fma_f32 v[66:67], v[18:19], v[66:67], v[96:97]
	v_lshlrev_b32_e32 v92, 16, v40
	v_and_b32_e32 v93, 0xffff0000, v40
	v_lshlrev_b32_e32 v94, 16, v41
	v_and_b32_e32 v95, 0xffff0000, v41
	v_lshl_add_u64 v[40:41], s[4:5], 0, v[38:39]
	v_lshl_add_u64 v[38:39], s[6:7], 0, v[38:39]
	v_pk_fma_f32 v[66:67], v[14:15], v[62:63], v[66:67]
	v_lshlrev_b32_e32 v64, 16, v55
	v_and_b32_e32 v65, 0xffff0000, v55
	v_lshlrev_b32_e32 v86, 16, v56
	v_and_b32_e32 v87, 0xffff0000, v56
	v_lshlrev_b32_e32 v88, 16, v57
	v_and_b32_e32 v89, 0xffff0000, v57
	global_load_dwordx4 v[54:57], v[38:39], off
	s_nop 0
	global_load_dwordx4 v[38:41], v[40:41], off
	v_pk_mul_f32 v[98:99], v[24:25], v[82:83]
	v_pk_mul_f32 v[58:59], v[66:67], v[58:59]
	v_pk_mul_f32 v[66:67], v[10:11], v[84:85]
	v_pk_fma_f32 v[68:69], v[20:21], v[68:69], v[98:99]
	v_pk_fma_f32 v[66:67], v[6:7], v[70:71], v[66:67]
	v_pk_fma_f32 v[68:69], v[16:17], v[64:65], v[68:69]
	v_pk_fma_f32 v[66:67], v[2:3], v[86:87], v[66:67]
	v_pk_mul_f32 v[60:61], v[68:69], v[60:61]
	v_pk_mul_f32 v[68:69], v[12:13], v[90:91]
	v_pk_mul_f32 v[66:67], v[66:67], v[92:93]
	v_pk_fma_f32 v[68:69], v[8:9], v[72:73], v[68:69]
	v_cvt_pk_bf16_f32 v58, v58, v59
	v_cvt_pk_bf16_f32 v59, v60, v61
	v_cvt_pk_bf16_f32 v60, v66, v67
	v_lshl_add_u64 v[66:67], v[76:77], 0, s[24:25]
	s_or_b32 s24, s14, 13
	v_pk_fma_f32 v[68:69], v[4:5], v[88:89], v[68:69]
	s_ashr_i32 s25, s24, 31
	v_pk_mul_f32 v[68:69], v[68:69], v[94:95]
	s_lshl_b64 s[24:25], s[24:25], 11
	v_cvt_pk_bf16_f32 v61, v68, v69
	global_store_dwordx4 v[66:67], v[58:61], off
	s_waitcnt vmcnt(10)
	v_lshlrev_b32_e32 v92, 16, v28
	v_and_b32_e32 v93, 0xffff0000, v28
	v_lshlrev_b32_e32 v58, 16, v26
	v_and_b32_e32 v59, 0xffff0000, v26
	v_lshlrev_b32_e32 v60, 16, v27
	v_and_b32_e32 v61, 0xffff0000, v27
	v_or_b32_e32 v26, s24, v74
	v_mov_b32_e32 v27, s25
	v_lshlrev_b32_e32 v94, 16, v29
	v_and_b32_e32 v95, 0xffff0000, v29
	v_lshl_add_u64 v[28:29], s[4:5], 0, v[26:27]
	v_lshl_add_u64 v[26:27], s[6:7], 0, v[26:27]
	v_pk_mul_f32 v[96:97], v[22:23], v[62:63]
	v_lshlrev_b32_e32 v66, 16, v42
	v_and_b32_e32 v67, 0xffff0000, v42
	v_lshlrev_b32_e32 v68, 16, v43
	v_and_b32_e32 v69, 0xffff0000, v43
	v_lshlrev_b32_e32 v70, 16, v44
	v_and_b32_e32 v71, 0xffff0000, v44
	v_lshlrev_b32_e32 v72, 16, v45
	v_and_b32_e32 v73, 0xffff0000, v45
	global_load_dwordx4 v[42:45], v[26:27], off
	s_nop 0
	global_load_dwordx4 v[26:29], v[28:29], off
	v_pk_fma_f32 v[80:81], v[18:19], v[80:81], v[96:97]
	v_pk_mul_f32 v[98:99], v[24:25], v[64:65]
	v_pk_fma_f32 v[80:81], v[14:15], v[66:67], v[80:81]
	v_pk_fma_f32 v[82:83], v[20:21], v[82:83], v[98:99]
	v_pk_mul_f32 v[58:59], v[80:81], v[58:59]
	v_pk_mul_f32 v[80:81], v[10:11], v[86:87]
	v_pk_fma_f32 v[82:83], v[16:17], v[68:69], v[82:83]
	v_pk_fma_f32 v[80:81], v[6:7], v[84:85], v[80:81]
	v_pk_mul_f32 v[60:61], v[82:83], v[60:61]
	v_pk_fma_f32 v[80:81], v[2:3], v[70:71], v[80:81]
	v_pk_mul_f32 v[82:83], v[12:13], v[88:89]
	v_pk_mul_f32 v[80:81], v[80:81], v[92:93]
	v_pk_fma_f32 v[82:83], v[8:9], v[90:91], v[82:83]
	v_cvt_pk_bf16_f32 v58, v58, v59
	v_cvt_pk_bf16_f32 v59, v60, v61
	v_cvt_pk_bf16_f32 v60, v80, v81
	v_lshl_add_u64 v[80:81], v[76:77], 0, s[16:17]
	s_or_b32 s16, s14, 14
	v_pk_fma_f32 v[82:83], v[4:5], v[72:73], v[82:83]
	s_ashr_i32 s17, s16, 31
	v_pk_mul_f32 v[82:83], v[82:83], v[94:95]
	s_lshl_b64 s[16:17], s[16:17], 11
	v_cvt_pk_bf16_f32 v61, v82, v83
	global_store_dwordx4 v[80:81], v[58:61], off
	s_waitcnt vmcnt(10)
	v_lshlrev_b32_e32 v92, 16, v32
	v_and_b32_e32 v93, 0xffff0000, v32
	v_lshlrev_b32_e32 v58, 16, v30
	v_and_b32_e32 v59, 0xffff0000, v30
	v_lshlrev_b32_e32 v60, 16, v31
	v_and_b32_e32 v61, 0xffff0000, v31
	v_or_b32_e32 v30, s16, v74
	v_mov_b32_e32 v31, s17
	v_lshlrev_b32_e32 v94, 16, v33
	v_and_b32_e32 v95, 0xffff0000, v33
	v_lshl_add_u64 v[32:33], s[4:5], 0, v[30:31]
	v_lshl_add_u64 v[30:31], s[6:7], 0, v[30:31]
	v_lshlrev_b32_e32 v80, 16, v46
	v_and_b32_e32 v81, 0xffff0000, v46
	v_lshlrev_b32_e32 v82, 16, v47
	v_and_b32_e32 v83, 0xffff0000, v47
	v_lshlrev_b32_e32 v84, 16, v48
	v_and_b32_e32 v85, 0xffff0000, v48
	v_lshlrev_b32_e32 v90, 16, v49
	v_and_b32_e32 v91, 0xffff0000, v49
	global_load_dwordx4 v[46:49], v[30:31], off
	s_nop 0
	global_load_dwordx4 v[30:33], v[32:33], off
	v_pk_mul_f32 v[96:97], v[22:23], v[66:67]
	v_pk_mul_f32 v[98:99], v[24:25], v[68:69]
	v_pk_fma_f32 v[62:63], v[18:19], v[62:63], v[96:97]
	v_pk_fma_f32 v[64:65], v[20:21], v[64:65], v[98:99]
	v_pk_fma_f32 v[62:63], v[14:15], v[80:81], v[62:63]
	v_pk_fma_f32 v[64:65], v[16:17], v[82:83], v[64:65]
	v_pk_mul_f32 v[58:59], v[62:63], v[58:59]
	v_pk_mul_f32 v[62:63], v[10:11], v[70:71]
	v_pk_mul_f32 v[60:61], v[64:65], v[60:61]
	v_pk_mul_f32 v[64:65], v[12:13], v[72:73]
	v_pk_fma_f32 v[62:63], v[6:7], v[86:87], v[62:63]
	v_pk_fma_f32 v[64:65], v[8:9], v[88:89], v[64:65]
	v_pk_fma_f32 v[62:63], v[2:3], v[84:85], v[62:63]
	s_or_b32 s14, s14, 15
	v_pk_fma_f32 v[64:65], v[4:5], v[90:91], v[64:65]
	v_pk_mul_f32 v[62:63], v[62:63], v[92:93]
	s_ashr_i32 s15, s14, 31
	v_pk_mul_f32 v[64:65], v[64:65], v[94:95]
	v_cvt_pk_bf16_f32 v58, v58, v59
	v_cvt_pk_bf16_f32 v59, v60, v61
	v_cvt_pk_bf16_f32 v60, v62, v63
	v_lshl_add_u64 v[62:63], v[76:77], 0, s[18:19]
	v_cvt_pk_bf16_f32 v61, v64, v65
	s_lshl_b64 s[14:15], s[14:15], 11
	global_store_dwordx4 v[62:63], v[58:61], off
	s_waitcnt vmcnt(10)
; __device__ __forceinline__ u32x4 pack8(const f32x4 a, const f32x4 b) { u32x4 w; w.x = cvt_pk_bf16(a[0], a[1]); w.y = cvt_pk_bf16(a[2], a[3]); w.z = cvt_pk_bf16(b[0], b[1]); w.w = cvt_pk_bf16(b[2], b[3]); return w; }
; __device__ __forceinline__ void p5_conv(const Args& A, int lane, int wave, bf16_t* Gout) {
;     ...
;         for (int t = 0; t < 32; ++t) { const size_t off = (size_t)(r0 + t) * DM + c0;
;             f32x4 ca, cb, ba, bb; pg8::unpack8(cq[t & 3], ca, cb); pg8::unpack8(bq[t & 3], ba, bb);
;             if (t + 4 < 32) { const size_t offn = (size_t)(r0 + t + 4) * DM + c0; cq[t & 3] = *(const u32x4*)(CU + offn); bq[t & 3] = *(const u32x4*)(BG + offn); }
;             const f32x4 oa = ba * ((w0a * p2a + w1a * p1a) + w2a * ca), ob = bb * ((w0b * p2b + w1b * p1b) + w2b * cb);
;             *(u32x4*)(Gout + off) = pg8::pack8(oa, ob);
;             p2a = p1a; p2b = p1b; p1a = ca; p1b = cb; }
	v_lshlrev_b32_e32 v92, 16, v36
	v_and_b32_e32 v93, 0xffff0000, v36
	v_lshlrev_b32_e32 v58, 16, v34
	v_and_b32_e32 v59, 0xffff0000, v34
	v_lshlrev_b32_e32 v60, 16, v35
	v_and_b32_e32 v61, 0xffff0000, v35
	v_or_b32_e32 v34, s14, v74
	v_mov_b32_e32 v35, s15
	v_lshlrev_b32_e32 v94, 16, v37
	v_and_b32_e32 v95, 0xffff0000, v37
	v_lshl_add_u64 v[36:37], s[4:5], 0, v[34:35]
	v_lshl_add_u64 v[34:35], s[6:7], 0, v[34:35]
	v_lshlrev_b32_e32 v62, 16, v50
	v_and_b32_e32 v63, 0xffff0000, v50
	v_lshlrev_b32_e32 v64, 16, v51
	v_and_b32_e32 v65, 0xffff0000, v51
	v_lshlrev_b32_e32 v86, 16, v52
	v_and_b32_e32 v87, 0xffff0000, v52
	v_lshlrev_b32_e32 v88, 16, v53
	v_and_b32_e32 v89, 0xffff0000, v53
	global_load_dwordx4 v[50:53], v[34:35], off
	s_nop 0
	global_load_dwordx4 v[34:37], v[36:37], off
	v_pk_mul_f32 v[96:97], v[22:23], v[80:81]
	v_pk_mul_f32 v[98:99], v[24:25], v[82:83]
	v_pk_fma_f32 v[66:67], v[18:19], v[66:67], v[96:97]
	v_pk_fma_f32 v[68:69], v[20:21], v[68:69], v[98:99]
	v_pk_fma_f32 v[66:67], v[14:15], v[62:63], v[66:67]
	v_pk_fma_f32 v[68:69], v[16:17], v[64:65], v[68:69]
	v_pk_mul_f32 v[58:59], v[66:67], v[58:59]
	v_pk_mul_f32 v[66:67], v[10:11], v[84:85]
	v_pk_mul_f32 v[60:61], v[68:69], v[60:61]
	v_pk_mul_f32 v[68:69], v[12:13], v[90:91]
	v_pk_fma_f32 v[66:67], v[6:7], v[70:71], v[66:67]
	v_pk_fma_f32 v[68:69], v[8:9], v[72:73], v[68:69]
	v_pk_fma_f32 v[66:67], v[2:3], v[86:87], v[66:67]
	s_or_b32 s18, s30, 16
	v_pk_fma_f32 v[68:69], v[4:5], v[88:89], v[68:69]
	v_pk_mul_f32 v[66:67], v[66:67], v[92:93]
	s_ashr_i32 s19, s18, 31
	v_pk_mul_f32 v[68:69], v[68:69], v[94:95]
	v_cvt_pk_bf16_f32 v58, v58, v59
	v_cvt_pk_bf16_f32 v59, v60, v61
	v_cvt_pk_bf16_f32 v60, v66, v67
	v_lshl_add_u64 v[66:67], v[76:77], 0, s[20:21]
	v_cvt_pk_bf16_f32 v61, v68, v69
	s_lshl_b64 s[18:19], s[18:19], 11
	global_store_dwordx4 v[66:67], v[58:61], off
	s_waitcnt vmcnt(10)
	v_lshlrev_b32_e32 v92, 16, v40
	v_and_b32_e32 v93, 0xffff0000, v40
	v_lshlrev_b32_e32 v58, 16, v38
	v_and_b32_e32 v59, 0xffff0000, v38
	v_lshlrev_b32_e32 v60, 16, v39
	v_and_b32_e32 v61, 0xffff0000, v39
	v_or_b32_e32 v38, s18, v74
	v_mov_b32_e32 v39, s19
	v_lshlrev_b32_e32 v94, 16, v41
	v_and_b32_e32 v95, 0xffff0000, v41
	v_lshl_add_u64 v[40:41], s[4:5], 0, v[38:39]
	v_lshl_add_u64 v[38:39], s[6:7], 0, v[38:39]
	v_pk_mul_f32 v[96:97], v[22:23], v[62:63]
	v_lshlrev_b32_e32 v66, 16, v54
	v_and_b32_e32 v67, 0xffff0000, v54
	v_lshlrev_b32_e32 v68, 16, v55
	v_and_b32_e32 v69, 0xffff0000, v55
	v_lshlrev_b32_e32 v70, 16, v56
	v_and_b32_e32 v71, 0xffff0000, v56
	v_lshlrev_b32_e32 v72, 16, v57
	v_and_b32_e32 v73, 0xffff0000, v57
	global_load_dwordx4 v[54:57], v[38:39], off
	s_nop 0
	global_load_dwordx4 v[38:41], v[40:41], off
	v_pk_mul_f32 v[98:99], v[24:25], v[64:65]
	v_pk_fma_f32 v[80:81], v[18:19], v[80:81], v[96:97]
	v_pk_fma_f32 v[82:83], v[20:21], v[82:83], v[98:99]
	v_pk_fma_f32 v[80:81], v[14:15], v[66:67], v[80:81]
	v_pk_fma_f32 v[82:83], v[16:17], v[68:69], v[82:83]
	v_pk_mul_f32 v[58:59], v[80:81], v[58:59]
	v_pk_mul_f32 v[80:81], v[10:11], v[86:87]
	v_pk_mul_f32 v[60:61], v[82:83], v[60:61]
	v_pk_mul_f32 v[82:83], v[12:13], v[88:89]
	v_pk_fma_f32 v[80:81], v[6:7], v[84:85], v[80:81]
	v_pk_fma_f32 v[82:83], v[8:9], v[90:91], v[82:83]
	v_pk_fma_f32 v[80:81], v[2:3], v[70:71], v[80:81]
	s_or_b32 s20, s30, 17
	v_pk_fma_f32 v[82:83], v[4:5], v[72:73], v[82:83]
	v_pk_mul_f32 v[80:81], v[80:81], v[92:93]
	s_ashr_i32 s21, s20, 31
	v_pk_mul_f32 v[82:83], v[82:83], v[94:95]
	v_cvt_pk_bf16_f32 v58, v58, v59
	v_cvt_pk_bf16_f32 v59, v60, v61
	v_cvt_pk_bf16_f32 v60, v80, v81
	v_lshl_add_u64 v[80:81], v[76:77], 0, s[22:23]
	v_cvt_pk_bf16_f32 v61, v82, v83
	s_lshl_b64 s[20:21], s[20:21], 11
	global_store_dwordx4 v[80:81], v[58:61], off
	s_waitcnt vmcnt(10)
	v_lshlrev_b32_e32 v92, 16, v28
	v_and_b32_e32 v93, 0xffff0000, v28
	v_lshlrev_b32_e32 v58, 16, v26
	v_and_b32_e32 v59, 0xffff0000, v26
	v_lshlrev_b32_e32 v60, 16, v27
	v_and_b32_e32 v61, 0xffff0000, v27
	v_or_b32_e32 v26, s20, v74
	v_mov_b32_e32 v27, s21
	v_lshlrev_b32_e32 v94, 16, v29
	v_and_b32_e32 v95, 0xffff0000, v29
	v_lshl_add_u64 v[28:29], s[4:5], 0, v[26:27]
	v_lshl_add_u64 v[26:27], s[6:7], 0, v[26:27]
	v_lshlrev_b32_e32 v80, 16, v42
	v_and_b32_e32 v81, 0xffff0000, v42
	v_lshlrev_b32_e32 v82, 16, v43
	v_and_b32_e32 v83, 0xffff0000, v43
	v_lshlrev_b32_e32 v84, 16, v44
	v_and_b32_e32 v85, 0xffff0000, v44
	v_lshlrev_b32_e32 v90, 16, v45
	v_and_b32_e32 v91, 0xffff0000, v45
	global_load_dwordx4 v[42:45], v[26:27], off
	s_nop 0
	global_load_dwordx4 v[26:29], v[28:29], off
	v_pk_mul_f32 v[96:97], v[22:23], v[66:67]
	v_pk_mul_f32 v[98:99], v[24:25], v[68:69]
	v_pk_fma_f32 v[62:63], v[18:19], v[62:63], v[96:97]
	v_pk_fma_f32 v[64:65], v[20:21], v[64:65], v[98:99]
	v_pk_fma_f32 v[62:63], v[14:15], v[80:81], v[62:63]
	v_pk_fma_f32 v[64:65], v[16:17], v[82:83], v[64:65]
	v_pk_mul_f32 v[58:59], v[62:63], v[58:59]
	v_pk_mul_f32 v[62:63], v[10:11], v[70:71]
	v_pk_mul_f32 v[60:61], v[64:65], v[60:61]
	v_pk_mul_f32 v[64:65], v[12:13], v[72:73]
	v_pk_fma_f32 v[62:63], v[6:7], v[86:87], v[62:63]
	v_pk_fma_f32 v[64:65], v[8:9], v[88:89], v[64:65]
	v_pk_fma_f32 v[62:63], v[2:3], v[84:85], v[62:63]
	s_or_b32 s22, s30, 18
	v_pk_fma_f32 v[64:65], v[4:5], v[90:91], v[64:65]
	v_pk_mul_f32 v[62:63], v[62:63], v[92:93]
	s_ashr_i32 s23, s22, 31
	v_pk_mul_f32 v[64:65], v[64:65], v[94:95]
	v_cvt_pk_bf16_f32 v58, v58, v59
	v_cvt_pk_bf16_f32 v59, v60, v61
	v_cvt_pk_bf16_f32 v60, v62, v63
	v_lshl_add_u64 v[62:63], v[76:77], 0, s[24:25]
	v_cvt_pk_bf16_f32 v61, v64, v65
	s_lshl_b64 s[22:23], s[22:23], 11
	global_store_dwordx4 v[62:63], v[58:61], off
	s_waitcnt vmcnt(10)
; __device__ __forceinline__ u32x4 pack8(const f32x4 a, const f32x4 b) { u32x4 w; w.x = cvt_pk_bf16(a[0], a[1]); w.y = cvt_pk_bf16(a[2], a[3]); w.z = cvt_pk_bf16(b[0], b[1]); w.w = cvt_pk_bf16(b[2], b[3]); return w; }
; __device__ __forceinline__ void p5_conv(const Args& A, int lane, int wave, bf16_t* Gout) {
;     ...
;         for (int t = 0; t < 32; ++t) { const size_t off = (size_t)(r0 + t) * DM + c0;
;             f32x4 ca, cb, ba, bb; pg8::unpack8(cq[t & 3], ca, cb); pg8::unpack8(bq[t & 3], ba, bb);
;             if (t + 4 < 32) { const size_t offn = (size_t)(r0 + t + 4) * DM + c0; cq[t & 3] = *(const u32x4*)(CU + offn); bq[t & 3] = *(const u32x4*)(BG + offn); }
;             const f32x4 oa = ba * ((w0a * p2a + w1a * p1a) + w2a * ca), ob = bb * ((w0b * p2b + w1b * p1b) + w2b * cb);
;             *(u32x4*)(Gout + off) = pg8::pack8(oa, ob);
;             p2a = p1a; p2b = p1b; p1a = ca; p1b = cb; }
	v_lshlrev_b32_e32 v92, 16, v32
	v_and_b32_e32 v93, 0xffff0000, v32
	v_lshlrev_b32_e32 v58, 16, v30
	v_and_b32_e32 v59, 0xffff0000, v30
	v_lshlrev_b32_e32 v60, 16, v31
	v_and_b32_e32 v61, 0xffff0000, v31
	v_or_b32_e32 v30, s22, v74
	v_mov_b32_e32 v31, s23
	v_lshlrev_b32_e32 v94, 16, v33
	v_and_b32_e32 v95, 0xffff0000, v33
	v_lshl_add_u64 v[32:33], s[4:5], 0, v[30:31]
	v_lshl_add_u64 v[30:31], s[6:7], 0, v[30:31]
	v_lshlrev_b32_e32 v62, 16, v46
	v_and_b32_e32 v63, 0xffff0000, v46
	v_lshlrev_b32_e32 v64, 16, v47
	v_and_b32_e32 v65, 0xffff0000, v47
	v_lshlrev_b32_e32 v86, 16, v48
	v_and_b32_e32 v87, 0xffff0000, v48
	v_lshlrev_b32_e32 v88, 16, v49
	v_and_b32_e32 v89, 0xffff0000, v49
	global_load_dwordx4 v[46:49], v[30:31], off
	s_nop 0
	global_load_dwordx4 v[30:33], v[32:33], off
	v_pk_mul_f32 v[96:97], v[22:23], v[80:81]
	v_pk_mul_f32 v[98:99], v[24:25], v[82:83]
	v_pk_fma_f32 v[66:67], v[18:19], v[66:67], v[96:97]
	v_pk_fma_f32 v[68:69], v[20:21], v[68:69], v[98:99]
	v_pk_fma_f32 v[66:67], v[14:15], v[62:63], v[66:67]
	v_pk_fma_f32 v[68:69], v[16:17], v[64:65], v[68:69]
	v_pk_mul_f32 v[58:59], v[66:67], v[58:59]
	v_pk_mul_f32 v[66:67], v[10:11], v[84:85]
	v_pk_mul_f32 v[60:61], v[68:69], v[60:61]
	v_pk_fma_f32 v[66:67], v[6:7], v[70:71], v[66:67]
	v_pk_mul_f32 v[68:69], v[12:13], v[90:91]
	v_pk_fma_f32 v[66:67], v[2:3], v[86:87], v[66:67]
	v_pk_fma_f32 v[68:69], v[8:9], v[72:73], v[68:69]
	v_pk_mul_f32 v[66:67], v[66:67], v[92:93]
	v_cvt_pk_bf16_f32 v58, v58, v59
	v_cvt_pk_bf16_f32 v59, v60, v61
	v_pk_fma_f32 v[68:69], v[4:5], v[88:89], v[68:69]
	v_cvt_pk_bf16_f32 v60, v66, v67
	v_lshl_add_u64 v[66:67], v[76:77], 0, s[16:17]
	s_or_b32 s16, s30, 19
	s_ashr_i32 s17, s16, 31
	v_pk_mul_f32 v[68:69], v[68:69], v[94:95]
	s_lshl_b64 s[16:17], s[16:17], 11
	v_cvt_pk_bf16_f32 v61, v68, v69
	global_store_dwordx4 v[66:67], v[58:61], off
	s_waitcnt vmcnt(10)
	v_lshlrev_b32_e32 v66, 16, v36
	v_and_b32_e32 v67, 0xffff0000, v36
	v_lshlrev_b32_e32 v58, 16, v34
	v_and_b32_e32 v59, 0xffff0000, v34
	v_lshlrev_b32_e32 v60, 16, v35
	v_and_b32_e32 v61, 0xffff0000, v35
	v_or_b32_e32 v34, s16, v74
	v_mov_b32_e32 v35, s17
	v_lshlrev_b32_e32 v68, 16, v37
	v_and_b32_e32 v69, 0xffff0000, v37
	v_lshl_add_u64 v[36:37], s[4:5], 0, v[34:35]
	v_lshl_add_u64 v[34:35], s[6:7], 0, v[34:35]
	v_lshlrev_b32_e32 v70, 16, v50
	v_and_b32_e32 v71, 0xffff0000, v50
	v_lshlrev_b32_e32 v72, 16, v51
	v_and_b32_e32 v73, 0xffff0000, v51
	v_lshlrev_b32_e32 v92, 16, v52
	v_and_b32_e32 v93, 0xffff0000, v52
	v_lshlrev_b32_e32 v94, 16, v53
	v_and_b32_e32 v95, 0xffff0000, v53
	global_load_dwordx4 v[50:53], v[34:35], off
	s_nop 0
	global_load_dwordx4 v[34:37], v[36:37], off
	v_pk_mul_f32 v[96:97], v[22:23], v[62:63]
	v_pk_mul_f32 v[98:99], v[24:25], v[64:65]
	v_pk_fma_f32 v[80:81], v[18:19], v[80:81], v[96:97]
	v_pk_fma_f32 v[82:83], v[20:21], v[82:83], v[98:99]
	v_pk_fma_f32 v[80:81], v[14:15], v[70:71], v[80:81]
	v_pk_fma_f32 v[82:83], v[16:17], v[72:73], v[82:83]
	v_pk_mul_f32 v[58:59], v[80:81], v[58:59]
	v_pk_mul_f32 v[80:81], v[10:11], v[86:87]
	v_pk_mul_f32 v[60:61], v[82:83], v[60:61]
	v_pk_fma_f32 v[80:81], v[6:7], v[84:85], v[80:81]
	v_pk_mul_f32 v[82:83], v[12:13], v[88:89]
	v_pk_fma_f32 v[80:81], v[2:3], v[92:93], v[80:81]
	v_pk_fma_f32 v[82:83], v[8:9], v[90:91], v[82:83]
	v_pk_mul_f32 v[66:67], v[80:81], v[66:67]
	v_cvt_pk_bf16_f32 v58, v58, v59
	v_cvt_pk_bf16_f32 v59, v60, v61
	v_pk_fma_f32 v[82:83], v[4:5], v[94:95], v[82:83]
	v_cvt_pk_bf16_f32 v60, v66, v67
	v_lshl_add_u64 v[66:67], v[76:77], 0, s[14:15]
	s_or_b32 s14, s30, 20
	s_ashr_i32 s15, s14, 31
	v_pk_mul_f32 v[68:69], v[82:83], v[68:69]
	s_lshl_b64 s[14:15], s[14:15], 11
	v_cvt_pk_bf16_f32 v61, v68, v69
	global_store_dwordx4 v[66:67], v[58:61], off
	v_pk_mul_f32 v[96:97], v[22:23], v[70:71]
	s_waitcnt vmcnt(11)
	v_lshlrev_b32_e32 v80, 16, v54
	s_waitcnt vmcnt(10)
	v_lshlrev_b32_e32 v58, 16, v38
	v_and_b32_e32 v59, 0xffff0000, v38
	v_lshlrev_b32_e32 v60, 16, v39
	v_and_b32_e32 v61, 0xffff0000, v39
	v_or_b32_e32 v38, s14, v74
	v_mov_b32_e32 v39, s15
	v_and_b32_e32 v81, 0xffff0000, v54
	v_lshlrev_b32_e32 v66, 16, v40
	v_and_b32_e32 v67, 0xffff0000, v40
	v_lshlrev_b32_e32 v68, 16, v41
	v_and_b32_e32 v69, 0xffff0000, v41
	v_lshl_add_u64 v[40:41], s[4:5], 0, v[38:39]
	v_lshl_add_u64 v[38:39], s[6:7], 0, v[38:39]
	v_pk_fma_f32 v[62:63], v[18:19], v[62:63], v[96:97]
	v_lshlrev_b32_e32 v82, 16, v55
	v_and_b32_e32 v83, 0xffff0000, v55
	v_lshlrev_b32_e32 v84, 16, v56
	v_and_b32_e32 v85, 0xffff0000, v56
	v_lshlrev_b32_e32 v90, 16, v57
	v_and_b32_e32 v91, 0xffff0000, v57
	global_load_dwordx4 v[54:57], v[38:39], off
	s_nop 0
	global_load_dwordx4 v[38:41], v[40:41], off
	v_pk_mul_f32 v[98:99], v[24:25], v[72:73]
	v_pk_fma_f32 v[62:63], v[14:15], v[80:81], v[62:63]
	v_pk_fma_f32 v[64:65], v[20:21], v[64:65], v[98:99]
	v_pk_mul_f32 v[58:59], v[62:63], v[58:59]
	v_pk_mul_f32 v[62:63], v[10:11], v[92:93]
	v_pk_fma_f32 v[64:65], v[16:17], v[82:83], v[64:65]
	v_pk_fma_f32 v[62:63], v[6:7], v[86:87], v[62:63]
	v_pk_mul_f32 v[60:61], v[64:65], v[60:61]
	v_pk_mul_f32 v[64:65], v[12:13], v[94:95]
	v_pk_fma_f32 v[62:63], v[2:3], v[84:85], v[62:63]
	v_pk_fma_f32 v[64:65], v[8:9], v[88:89], v[64:65]
	v_pk_mul_f32 v[62:63], v[62:63], v[66:67]
	v_pk_fma_f32 v[64:65], v[4:5], v[90:91], v[64:65]
	v_cvt_pk_bf16_f32 v58, v58, v59
	v_cvt_pk_bf16_f32 v59, v60, v61
	v_cvt_pk_bf16_f32 v60, v62, v63
	v_lshl_add_u64 v[62:63], v[76:77], 0, s[18:19]
	v_pk_mul_f32 v[96:97], v[22:23], v[80:81]
	v_pk_mul_f32 v[64:65], v[64:65], v[68:69]
	s_or_b32 s18, s30, 21
	v_cvt_pk_bf16_f32 v61, v64, v65
	global_store_dwordx4 v[62:63], v[58:61], off
	s_waitcnt vmcnt(11)
; __device__ __forceinline__ u32x4 pack8(const f32x4 a, const f32x4 b) { u32x4 w; w.x = cvt_pk_bf16(a[0], a[1]); w.y = cvt_pk_bf16(a[2], a[3]); w.z = cvt_pk_bf16(b[0], b[1]); w.w = cvt_pk_bf16(b[2], b[3]); return w; }
; __device__ __forceinline__ void p5_conv(const Args& A, int lane, int wave, bf16_t* Gout) {
;     ...
;         for (int t = 0; t < 32; ++t) { const size_t off = (size_t)(r0 + t) * DM + c0;
;             f32x4 ca, cb, ba, bb; pg8::unpack8(cq[t & 3], ca, cb); pg8::unpack8(bq[t & 3], ba, bb);
;             if (t + 4 < 32) { const size_t offn = (size_t)(r0 + t + 4) * DM + c0; cq[t & 3] = *(const u32x4*)(CU + offn); bq[t & 3] = *(const u32x4*)(BG + offn); }
;             const f32x4 oa = ba * ((w0a * p2a + w1a * p1a) + w2a * ca), ob = bb * ((w0b * p2b + w1b * p1b) + w2b * cb);
;             *(u32x4*)(Gout + off) = pg8::pack8(oa, ob);
;             p2a = p1a; p2b = p1b; p1a = ca; p1b = cb; }
	v_lshlrev_b32_e32 v62, 16, v42
	v_and_b32_e32 v63, 0xffff0000, v42
	v_pk_fma_f32 v[70:71], v[18:19], v[70:71], v[96:97]
	v_lshlrev_b32_e32 v64, 16, v43
	v_and_b32_e32 v65, 0xffff0000, v43
	s_waitcnt vmcnt(10)
	v_lshlrev_b32_e32 v42, 16, v26
	v_and_b32_e32 v43, 0xffff0000, v26
	s_ashr_i32 s19, s18, 31
	v_pk_fma_f32 v[70:71], v[14:15], v[62:63], v[70:71]
	s_lshl_b64 s[18:19], s[18:19], 11
	v_pk_mul_f32 v[98:99], v[24:25], v[82:83]
	v_pk_mul_f32 v[42:43], v[70:71], v[42:43]
	v_pk_mul_f32 v[70:71], v[10:11], v[84:85]
	v_lshlrev_b32_e32 v86, 16, v44
	v_and_b32_e32 v87, 0xffff0000, v44
	v_lshlrev_b32_e32 v88, 16, v45
	v_and_b32_e32 v89, 0xffff0000, v45
	v_lshlrev_b32_e32 v44, 16, v27
	v_and_b32_e32 v45, 0xffff0000, v27
	v_or_b32_e32 v26, s18, v74
	v_mov_b32_e32 v27, s19
	v_pk_fma_f32 v[72:73], v[20:21], v[72:73], v[98:99]
	v_pk_fma_f32 v[70:71], v[6:7], v[92:93], v[70:71]
	v_lshlrev_b32_e32 v58, 16, v28
	v_and_b32_e32 v59, 0xffff0000, v28
	v_lshlrev_b32_e32 v60, 16, v29
	v_and_b32_e32 v61, 0xffff0000, v29
	v_lshl_add_u64 v[28:29], s[4:5], 0, v[26:27]
	v_lshl_add_u64 v[26:27], s[6:7], 0, v[26:27]
	v_pk_fma_f32 v[72:73], v[16:17], v[64:65], v[72:73]
	v_pk_fma_f32 v[70:71], v[2:3], v[86:87], v[70:71]
	global_load_dwordx4 v[66:69], v[26:27], off
	s_nop 0
	global_load_dwordx4 v[26:29], v[28:29], off
	v_pk_mul_f32 v[44:45], v[72:73], v[44:45]
	v_pk_mul_f32 v[58:59], v[70:71], v[58:59]
	v_pk_mul_f32 v[72:73], v[12:13], v[90:91]
	v_cvt_pk_bf16_f32 v42, v42, v43
	v_cvt_pk_bf16_f32 v43, v44, v45
	v_cvt_pk_bf16_f32 v44, v58, v59
	v_lshl_add_u64 v[58:59], v[76:77], 0, s[20:21]
	s_or_b32 s20, s30, 22
	v_pk_fma_f32 v[72:73], v[8:9], v[94:95], v[72:73]
	s_ashr_i32 s21, s20, 31
	v_pk_fma_f32 v[72:73], v[4:5], v[88:89], v[72:73]
	s_lshl_b64 s[20:21], s[20:21], 11
	v_pk_mul_f32 v[60:61], v[72:73], v[60:61]
	s_waitcnt vmcnt(10)
	v_lshlrev_b32_e32 v92, 16, v46
	v_cvt_pk_bf16_f32 v45, v60, v61
	global_store_dwordx4 v[58:59], v[42:45], off
	v_and_b32_e32 v93, 0xffff0000, v46
	v_lshlrev_b32_e32 v94, 16, v47
	v_or_b32_e32 v42, s20, v74
	v_mov_b32_e32 v43, s21
	v_lshl_add_u64 v[44:45], s[4:5], 0, v[42:43]
	v_lshl_add_u64 v[42:43], s[6:7], 0, v[42:43]
	v_and_b32_e32 v95, 0xffff0000, v47
	v_lshlrev_b32_e32 v96, 16, v48
	v_and_b32_e32 v97, 0xffff0000, v48
	v_lshlrev_b32_e32 v98, 16, v49
	v_and_b32_e32 v99, 0xffff0000, v49
	global_load_dwordx4 v[46:49], v[42:43], off
	s_nop 0
	global_load_dwordx4 v[42:45], v[44:45], off
	v_pk_mul_f32 v[70:71], v[22:23], v[62:63]
	v_pk_mul_f32 v[72:73], v[24:25], v[64:65]
	v_pk_fma_f32 v[70:71], v[18:19], v[80:81], v[70:71]
	v_pk_fma_f32 v[72:73], v[20:21], v[82:83], v[72:73]
	s_waitcnt vmcnt(12)
	v_lshlrev_b32_e32 v58, 16, v30
	v_and_b32_e32 v59, 0xffff0000, v30
	v_lshlrev_b32_e32 v30, 16, v31
	v_and_b32_e32 v31, 0xffff0000, v31
	v_pk_fma_f32 v[70:71], v[14:15], v[92:93], v[70:71]
	v_pk_fma_f32 v[72:73], v[16:17], v[94:95], v[72:73]
	v_lshlrev_b32_e32 v60, 16, v32
	v_pk_mul_f32 v[72:73], v[72:73], v[30:31]
	v_pk_mul_f32 v[30:31], v[70:71], v[58:59]
	v_pk_mul_f32 v[58:59], v[10:11], v[86:87]
	v_pk_mul_f32 v[70:71], v[12:13], v[88:89]
	v_pk_fma_f32 v[58:59], v[6:7], v[84:85], v[58:59]
	v_pk_fma_f32 v[70:71], v[8:9], v[90:91], v[70:71]
	v_and_b32_e32 v61, 0xffff0000, v32
	v_lshlrev_b32_e32 v32, 16, v33
	v_and_b32_e32 v33, 0xffff0000, v33
	v_pk_fma_f32 v[58:59], v[2:3], v[96:97], v[58:59]
	v_pk_fma_f32 v[70:71], v[4:5], v[98:99], v[70:71]
	s_waitcnt vmcnt(10)
	v_lshlrev_b32_e32 v80, 16, v50
	v_pk_mul_f32 v[70:71], v[70:71], v[32:33]
	v_pk_mul_f32 v[32:33], v[58:59], v[60:61]
	v_lshl_add_u64 v[58:59], v[76:77], 0, s[22:23]
	s_or_b32 s22, s30, 23
	s_ashr_i32 s23, s22, 31
	s_lshl_b64 s[22:23], s[22:23], 11
	v_and_b32_e32 v81, 0xffff0000, v50
	v_lshlrev_b32_e32 v82, 16, v51
	v_and_b32_e32 v83, 0xffff0000, v51
	v_or_b32_e32 v50, s22, v74
	v_mov_b32_e32 v51, s23
	v_cvt_pk_bf16_f32 v30, v30, v31
	v_cvt_pk_bf16_f32 v31, v72, v73
	v_cvt_pk_bf16_f32 v32, v32, v33
	v_cvt_pk_bf16_f32 v33, v70, v71
	global_store_dwordx4 v[58:59], v[30:33], off
	v_lshlrev_b32_e32 v84, 16, v52
	v_and_b32_e32 v85, 0xffff0000, v52
	v_lshlrev_b32_e32 v90, 16, v53
	v_and_b32_e32 v91, 0xffff0000, v53
	v_lshl_add_u64 v[52:53], s[4:5], 0, v[50:51]
	v_lshl_add_u64 v[50:51], s[6:7], 0, v[50:51]
	global_load_dwordx4 v[70:73], v[50:51], off
	global_load_dwordx4 v[58:61], v[52:53], off
	v_pk_mul_f32 v[50:51], v[22:23], v[92:93]
	s_waitcnt vmcnt(12)
	v_lshlrev_b32_e32 v30, 16, v34
	v_pk_fma_f32 v[50:51], v[18:19], v[62:63], v[50:51]
	v_and_b32_e32 v31, 0xffff0000, v34
	v_pk_fma_f32 v[50:51], v[14:15], v[80:81], v[50:51]
	v_pk_mul_f32 v[52:53], v[24:25], v[94:95]
	v_pk_mul_f32 v[30:31], v[50:51], v[30:31]
	v_pk_mul_f32 v[50:51], v[10:11], v[96:97]
	v_pk_fma_f32 v[52:53], v[20:21], v[64:65], v[52:53]
	v_pk_fma_f32 v[50:51], v[6:7], v[86:87], v[50:51]
	v_lshlrev_b32_e32 v32, 16, v35
	v_and_b32_e32 v33, 0xffff0000, v35
	v_lshlrev_b32_e32 v34, 16, v36
	v_and_b32_e32 v35, 0xffff0000, v36
	v_pk_fma_f32 v[52:53], v[16:17], v[82:83], v[52:53]
	v_pk_fma_f32 v[50:51], v[2:3], v[84:85], v[50:51]
	v_pk_mul_f32 v[32:33], v[52:53], v[32:33]
	v_pk_mul_f32 v[52:53], v[12:13], v[98:99]
	v_pk_mul_f32 v[34:35], v[50:51], v[34:35]
	v_pk_fma_f32 v[52:53], v[8:9], v[88:89], v[52:53]
	v_cvt_pk_bf16_f32 v30, v30, v31
	v_cvt_pk_bf16_f32 v31, v32, v33
	v_cvt_pk_bf16_f32 v32, v34, v35
	v_lshl_add_u64 v[34:35], v[76:77], 0, s[16:17]
	s_add_u32 s16, s14, 0x2000
	v_lshlrev_b32_e32 v36, 16, v37
	v_and_b32_e32 v37, 0xffff0000, v37
	v_pk_fma_f32 v[52:53], v[4:5], v[90:91], v[52:53]
	s_addc_u32 s17, s15, 0
	v_pk_mul_f32 v[36:37], v[52:53], v[36:37]
	v_pk_mul_f32 v[50:51], v[22:23], v[80:81]
	v_cvt_pk_bf16_f32 v33, v36, v37
	global_store_dwordx4 v[34:35], v[30:33], off
	s_waitcnt vmcnt(11)
; __device__ __forceinline__ u32x4 pack8(const f32x4 a, const f32x4 b) { u32x4 w; w.x = cvt_pk_bf16(a[0], a[1]); w.y = cvt_pk_bf16(a[2], a[3]); w.z = cvt_pk_bf16(b[0], b[1]); w.w = cvt_pk_bf16(b[2], b[3]); return w; }
; __device__ __forceinline__ void p5_conv(const Args& A, int lane, int wave, bf16_t* Gout) {
;     ...
;         for (int t = 0; t < 32; ++t) { const size_t off = (size_t)(r0 + t) * DM + c0;
;             f32x4 ca, cb, ba, bb; pg8::unpack8(cq[t & 3], ca, cb); pg8::unpack8(bq[t & 3], ba, bb);
;             if (t + 4 < 32) { const size_t offn = (size_t)(r0 + t + 4) * DM + c0; cq[t & 3] = *(const u32x4*)(CU + offn); bq[t & 3] = *(const u32x4*)(BG + offn); }
;             const f32x4 oa = ba * ((w0a * p2a + w1a * p1a) + w2a * ca), ob = bb * ((w0b * p2b + w1b * p1b) + w2b * cb);
;             *(u32x4*)(Gout + off) = pg8::pack8(oa, ob);
;             p2a = p1a; p2b = p1b; p1a = ca; p1b = cb; }
	v_lshlrev_b32_e32 v86, 16, v54
	v_and_b32_e32 v87, 0xffff0000, v54
	v_or_b32_e32 v30, s16, v74
	v_mov_b32_e32 v31, s17
	v_lshl_add_u64 v[32:33], s[4:5], 0, v[30:31]
	v_lshl_add_u64 v[30:31], s[6:7], 0, v[30:31]
	global_load_dwordx4 v[62:65], v[30:31], off
	s_nop 0
	global_load_dwordx4 v[30:33], v[32:33], off
	v_pk_fma_f32 v[50:51], v[18:19], v[92:93], v[50:51]
	s_waitcnt vmcnt(12)
	v_lshlrev_b32_e32 v34, 16, v38
	v_and_b32_e32 v35, 0xffff0000, v38
	v_pk_fma_f32 v[50:51], v[14:15], v[86:87], v[50:51]
	v_pk_mul_f32 v[52:53], v[24:25], v[82:83]
	v_pk_mul_f32 v[34:35], v[50:51], v[34:35]
	v_pk_mul_f32 v[50:51], v[10:11], v[84:85]
	v_lshlrev_b32_e32 v88, 16, v55
	v_and_b32_e32 v89, 0xffff0000, v55
	v_lshlrev_b32_e32 v100, 16, v56
	v_and_b32_e32 v101, 0xffff0000, v56
	v_pk_fma_f32 v[52:53], v[20:21], v[94:95], v[52:53]
	v_pk_fma_f32 v[50:51], v[6:7], v[96:97], v[50:51]
	v_lshlrev_b32_e32 v36, 16, v39
	v_and_b32_e32 v37, 0xffff0000, v39
	v_lshlrev_b32_e32 v38, 16, v40
	v_and_b32_e32 v39, 0xffff0000, v40
	v_pk_fma_f32 v[52:53], v[16:17], v[88:89], v[52:53]
	v_pk_fma_f32 v[50:51], v[2:3], v[100:101], v[50:51]
	v_pk_mul_f32 v[36:37], v[52:53], v[36:37]
	v_pk_mul_f32 v[52:53], v[12:13], v[90:91]
	v_pk_mul_f32 v[38:39], v[50:51], v[38:39]
	v_lshlrev_b32_e32 v102, 16, v57
	v_and_b32_e32 v103, 0xffff0000, v57
	v_pk_fma_f32 v[52:53], v[8:9], v[98:99], v[52:53]
	v_cvt_pk_bf16_f32 v34, v34, v35
	v_cvt_pk_bf16_f32 v35, v36, v37
	v_cvt_pk_bf16_f32 v36, v38, v39
	v_lshl_add_u64 v[38:39], v[76:77], 0, s[14:15]
	s_add_u32 s14, s18, 0x2000
	v_lshlrev_b32_e32 v40, 16, v41
	v_and_b32_e32 v41, 0xffff0000, v41
	v_pk_fma_f32 v[52:53], v[4:5], v[102:103], v[52:53]
	s_addc_u32 s15, s19, 0
	v_pk_mul_f32 v[40:41], v[52:53], v[40:41]
	s_waitcnt vmcnt(10)
	v_lshlrev_b32_e32 v92, 16, v66
	v_cvt_pk_bf16_f32 v37, v40, v41
	global_store_dwordx4 v[38:39], v[34:37], off
	v_or_b32_e32 v38, s14, v74
	v_mov_b32_e32 v39, s15
	v_lshl_add_u64 v[40:41], s[4:5], 0, v[38:39]
	v_lshl_add_u64 v[38:39], s[6:7], 0, v[38:39]
	global_load_dwordx4 v[54:57], v[38:39], off
	global_load_dwordx4 v[50:53], v[40:41], off
	v_pk_mul_f32 v[38:39], v[22:23], v[86:87]
	v_pk_mul_f32 v[40:41], v[24:25], v[88:89]
	v_and_b32_e32 v93, 0xffff0000, v66
	v_lshlrev_b32_e32 v66, 16, v67
	v_and_b32_e32 v67, 0xffff0000, v67
	v_pk_fma_f32 v[40:41], v[20:21], v[82:83], v[40:41]
	v_pk_fma_f32 v[38:39], v[18:19], v[80:81], v[38:39]
	s_waitcnt vmcnt(12)
	v_lshlrev_b32_e32 v34, 16, v26
	v_and_b32_e32 v35, 0xffff0000, v26
	v_lshlrev_b32_e32 v26, 16, v27
	v_and_b32_e32 v27, 0xffff0000, v27
	v_pk_fma_f32 v[38:39], v[14:15], v[92:93], v[38:39]
	v_pk_fma_f32 v[40:41], v[16:17], v[66:67], v[40:41]
	v_lshlrev_b32_e32 v94, 16, v68
	v_pk_mul_f32 v[40:41], v[40:41], v[26:27]
	v_pk_mul_f32 v[26:27], v[38:39], v[34:35]
	v_pk_mul_f32 v[34:35], v[10:11], v[100:101]
	v_pk_mul_f32 v[38:39], v[12:13], v[102:103]
	v_and_b32_e32 v95, 0xffff0000, v68
	v_lshlrev_b32_e32 v68, 16, v69
	v_and_b32_e32 v69, 0xffff0000, v69
	v_pk_fma_f32 v[38:39], v[8:9], v[90:91], v[38:39]
	v_pk_fma_f32 v[34:35], v[6:7], v[84:85], v[34:35]
	v_lshlrev_b32_e32 v36, 16, v28
	v_and_b32_e32 v37, 0xffff0000, v28
	v_lshlrev_b32_e32 v28, 16, v29
	v_and_b32_e32 v29, 0xffff0000, v29
	v_pk_fma_f32 v[34:35], v[2:3], v[94:95], v[34:35]
	v_pk_fma_f32 v[38:39], v[4:5], v[68:69], v[38:39]
	s_add_u32 s14, s20, 0x2000
	v_pk_mul_f32 v[38:39], v[38:39], v[28:29]
	v_pk_mul_f32 v[28:29], v[34:35], v[36:37]
	v_lshl_add_u64 v[34:35], v[76:77], 0, s[18:19]
	s_addc_u32 s15, s21, 0
	v_cvt_pk_bf16_f32 v26, v26, v27
	v_cvt_pk_bf16_f32 v27, v40, v41
	v_cvt_pk_bf16_f32 v28, v28, v29
	v_cvt_pk_bf16_f32 v29, v38, v39
	global_store_dwordx4 v[34:35], v[26:29], off
	v_or_b32_e32 v34, s14, v74
	v_mov_b32_e32 v35, s15
	s_waitcnt vmcnt(10)
	v_lshlrev_b32_e32 v26, 16, v42
	v_and_b32_e32 v27, 0xffff0000, v42
	v_lshlrev_b32_e32 v28, 16, v43
	v_and_b32_e32 v29, 0xffff0000, v43
	v_lshlrev_b32_e32 v38, 16, v44
	v_and_b32_e32 v39, 0xffff0000, v44
	v_lshlrev_b32_e32 v40, 16, v45
	v_and_b32_e32 v41, 0xffff0000, v45
	v_lshl_add_u64 v[42:43], s[4:5], 0, v[34:35]
	v_lshl_add_u64 v[44:45], s[6:7], 0, v[34:35]
	v_lshlrev_b32_e32 v80, 16, v46
	v_and_b32_e32 v81, 0xffff0000, v46
	v_lshlrev_b32_e32 v82, 16, v47
	v_and_b32_e32 v83, 0xffff0000, v47
	v_lshlrev_b32_e32 v84, 16, v48
	v_and_b32_e32 v85, 0xffff0000, v48
	v_lshlrev_b32_e32 v90, 16, v49
	v_and_b32_e32 v91, 0xffff0000, v49
	global_load_dwordx4 v[46:49], v[44:45], off
	global_load_dwordx4 v[34:37], v[42:43], off
	v_pk_mul_f32 v[42:43], v[22:23], v[92:93]
	v_pk_mul_f32 v[44:45], v[24:25], v[66:67]
	v_pk_fma_f32 v[42:43], v[18:19], v[86:87], v[42:43]
	v_pk_fma_f32 v[44:45], v[20:21], v[88:89], v[44:45]
	v_pk_fma_f32 v[42:43], v[14:15], v[80:81], v[42:43]
	v_pk_fma_f32 v[44:45], v[16:17], v[82:83], v[44:45]
	v_pk_mul_f32 v[26:27], v[42:43], v[26:27]
	v_pk_mul_f32 v[42:43], v[10:11], v[94:95]
	v_pk_mul_f32 v[28:29], v[44:45], v[28:29]
	v_pk_fma_f32 v[42:43], v[6:7], v[100:101], v[42:43]
	v_pk_mul_f32 v[44:45], v[12:13], v[68:69]
	v_pk_fma_f32 v[42:43], v[2:3], v[84:85], v[42:43]
	v_pk_fma_f32 v[44:45], v[8:9], v[102:103], v[44:45]
	v_pk_mul_f32 v[38:39], v[42:43], v[38:39]
	s_add_u32 s14, s22, 0x2000
	v_pk_fma_f32 v[44:45], v[4:5], v[90:91], v[44:45]
	v_cvt_pk_bf16_f32 v26, v26, v27
	v_cvt_pk_bf16_f32 v27, v28, v29
	v_cvt_pk_bf16_f32 v28, v38, v39
	v_lshl_add_u64 v[38:39], v[76:77], 0, s[20:21]
	s_addc_u32 s15, s23, 0
	v_pk_mul_f32 v[40:41], v[44:45], v[40:41]
	s_waitcnt vmcnt(10)
; __device__ __forceinline__ u32x4 pack8(const f32x4 a, const f32x4 b) { u32x4 w; w.x = cvt_pk_bf16(a[0], a[1]); w.y = cvt_pk_bf16(a[2], a[3]); w.z = cvt_pk_bf16(b[0], b[1]); w.w = cvt_pk_bf16(b[2], b[3]); return w; }
; __device__ __forceinline__ void p5_conv(const Args& A, int lane, int wave, bf16_t* Gout) {
;     ...
;         for (int t = 0; t < 32; ++t) { const size_t off = (size_t)(r0 + t) * DM + c0;
;             f32x4 ca, cb, ba, bb; pg8::unpack8(cq[t & 3], ca, cb); pg8::unpack8(bq[t & 3], ba, bb);
;             if (t + 4 < 32) { const size_t offn = (size_t)(r0 + t + 4) * DM + c0; cq[t & 3] = *(const u32x4*)(CU + offn); bq[t & 3] = *(const u32x4*)(BG + offn); }
;             const f32x4 oa = ba * ((w0a * p2a + w1a * p1a) + w2a * ca), ob = bb * ((w0b * p2b + w1b * p1b) + w2b * cb);
;             *(u32x4*)(Gout + off) = pg8::pack8(oa, ob);
;             p2a = p1a; p2b = p1b; p1a = ca; p1b = cb; }
	v_lshlrev_b32_e32 v86, 16, v70
	v_cvt_pk_bf16_f32 v29, v40, v41
	global_store_dwordx4 v[38:39], v[26:29], off
	v_and_b32_e32 v87, 0xffff0000, v70
	v_lshlrev_b32_e32 v70, 16, v71
	v_or_b32_e32 v26, s14, v74
	v_mov_b32_e32 v27, s15
	v_lshl_add_u64 v[98:99], s[6:7], 0, v[26:27]
	v_lshl_add_u64 v[96:97], s[4:5], 0, v[26:27]
	global_load_dwordx4 v[38:41], v[98:99], off
	global_load_dwordx4 v[26:29], v[96:97], off
	v_pk_mul_f32 v[98:99], v[24:25], v[82:83]
	v_and_b32_e32 v71, 0xffff0000, v71
	v_pk_mul_f32 v[96:97], v[22:23], v[80:81]
	v_pk_fma_f32 v[66:67], v[20:21], v[66:67], v[98:99]
	s_waitcnt vmcnt(12)
	v_lshlrev_b32_e32 v44, 16, v59
	v_and_b32_e32 v45, 0xffff0000, v59
	v_pk_fma_f32 v[92:93], v[18:19], v[92:93], v[96:97]
	v_pk_fma_f32 v[66:67], v[16:17], v[70:71], v[66:67]
	v_lshlrev_b32_e32 v42, 16, v58
	v_and_b32_e32 v43, 0xffff0000, v58
	v_pk_fma_f32 v[92:93], v[14:15], v[86:87], v[92:93]
	v_pk_mul_f32 v[44:45], v[66:67], v[44:45]
	v_pk_mul_f32 v[66:67], v[10:11], v[84:85]
	v_lshlrev_b32_e32 v88, 16, v72
	v_and_b32_e32 v89, 0xffff0000, v72
	v_pk_mul_f32 v[42:43], v[92:93], v[42:43]
	v_pk_mul_f32 v[92:93], v[12:13], v[90:91]
	v_pk_fma_f32 v[66:67], v[6:7], v[94:95], v[66:67]
	v_lshlrev_b32_e32 v72, 16, v73
	v_and_b32_e32 v73, 0xffff0000, v73
	v_lshlrev_b32_e32 v58, 16, v60
	v_and_b32_e32 v59, 0xffff0000, v60
	v_pk_fma_f32 v[68:69], v[8:9], v[68:69], v[92:93]
	v_pk_fma_f32 v[66:67], v[2:3], v[88:89], v[66:67]
	s_or_b32 s14, s30, 28
	v_lshlrev_b32_e32 v60, 16, v61
	v_and_b32_e32 v61, 0xffff0000, v61
	v_pk_fma_f32 v[68:69], v[4:5], v[72:73], v[68:69]
	v_pk_mul_f32 v[58:59], v[66:67], v[58:59]
	s_ashr_i32 s15, s14, 31
	v_pk_mul_f32 v[60:61], v[68:69], v[60:61]
	v_cvt_pk_bf16_f32 v42, v42, v43
	v_cvt_pk_bf16_f32 v43, v44, v45
	v_cvt_pk_bf16_f32 v44, v58, v59
	v_lshl_add_u64 v[58:59], v[76:77], 0, s[22:23]
	s_lshl_b64 s[14:15], s[14:15], 11
	v_cvt_pk_bf16_f32 v45, v60, v61
	global_store_dwordx4 v[58:59], v[42:45], off
	s_waitcnt vmcnt(10)
	v_lshlrev_b32_e32 v58, 16, v30
	v_and_b32_e32 v59, 0xffff0000, v30
	v_lshlrev_b32_e32 v60, 16, v31
	v_and_b32_e32 v61, 0xffff0000, v31
	v_or_b32_e32 v30, s14, v74
	v_mov_b32_e32 v31, s15
	v_lshl_add_u64 v[96:97], s[4:5], 0, v[30:31]
	v_lshl_add_u64 v[98:99], s[6:7], 0, v[30:31]
	v_lshlrev_b32_e32 v92, 16, v32
	v_and_b32_e32 v93, 0xffff0000, v32
	v_lshlrev_b32_e32 v94, 16, v33
	v_and_b32_e32 v95, 0xffff0000, v33
	global_load_dwordx4 v[42:45], v[98:99], off
	global_load_dwordx4 v[30:33], v[96:97], off
	v_pk_mul_f32 v[96:97], v[22:23], v[86:87]
	v_lshlrev_b32_e32 v66, 16, v62
	v_and_b32_e32 v67, 0xffff0000, v62
	v_pk_fma_f32 v[80:81], v[18:19], v[80:81], v[96:97]
	v_pk_mul_f32 v[98:99], v[24:25], v[70:71]
	v_pk_fma_f32 v[80:81], v[14:15], v[66:67], v[80:81]
	s_or_b32 s16, s30, 24
	v_pk_mul_f32 v[58:59], v[80:81], v[58:59]
	v_pk_mul_f32 v[80:81], v[10:11], v[88:89]
	v_lshlrev_b32_e32 v62, 16, v63
	v_and_b32_e32 v63, 0xffff0000, v63
	v_lshlrev_b32_e32 v68, 16, v64
	v_and_b32_e32 v69, 0xffff0000, v64
	v_pk_fma_f32 v[82:83], v[20:21], v[82:83], v[98:99]
	v_pk_fma_f32 v[80:81], v[6:7], v[84:85], v[80:81]
	s_ashr_i32 s17, s16, 31
	v_pk_fma_f32 v[82:83], v[16:17], v[62:63], v[82:83]
	v_pk_fma_f32 v[80:81], v[2:3], v[68:69], v[80:81]
	v_pk_mul_f32 v[60:61], v[82:83], v[60:61]
	v_pk_mul_f32 v[82:83], v[12:13], v[72:73]
	v_pk_mul_f32 v[80:81], v[80:81], v[92:93]
	s_lshl_b64 s[16:17], s[16:17], 11
	v_lshlrev_b32_e32 v64, 16, v65
	v_and_b32_e32 v65, 0xffff0000, v65
	v_pk_fma_f32 v[82:83], v[8:9], v[90:91], v[82:83]
	v_cvt_pk_bf16_f32 v58, v58, v59
	v_cvt_pk_bf16_f32 v59, v60, v61
	v_cvt_pk_bf16_f32 v60, v80, v81
	v_lshl_add_u64 v[80:81], v[76:77], 0, s[16:17]
	s_or_b32 s16, s30, 29
	v_pk_fma_f32 v[82:83], v[4:5], v[64:65], v[82:83]
	s_ashr_i32 s17, s16, 31
	v_pk_mul_f32 v[82:83], v[82:83], v[94:95]
	s_lshl_b64 s[16:17], s[16:17], 11
	v_cvt_pk_bf16_f32 v61, v82, v83
	global_store_dwordx4 v[80:81], v[58:61], off
	s_waitcnt vmcnt(11)
	v_lshlrev_b32_e32 v80, 16, v54
	v_and_b32_e32 v81, 0xffff0000, v54
	s_waitcnt vmcnt(10)
	v_lshlrev_b32_e32 v58, 16, v50
	v_and_b32_e32 v59, 0xffff0000, v50
	v_lshlrev_b32_e32 v60, 16, v51
	v_and_b32_e32 v61, 0xffff0000, v51
	v_or_b32_e32 v50, s16, v74
	v_mov_b32_e32 v51, s17
	v_lshl_add_u64 v[96:97], s[4:5], 0, v[50:51]
	v_lshl_add_u64 v[98:99], s[6:7], 0, v[50:51]
	v_lshlrev_b32_e32 v82, 16, v55
	v_and_b32_e32 v83, 0xffff0000, v55
	v_lshlrev_b32_e32 v84, 16, v56
	v_and_b32_e32 v85, 0xffff0000, v56
	v_lshlrev_b32_e32 v90, 16, v57
	v_and_b32_e32 v91, 0xffff0000, v57
	v_lshlrev_b32_e32 v92, 16, v52
	v_and_b32_e32 v93, 0xffff0000, v52
	v_lshlrev_b32_e32 v94, 16, v53
	v_and_b32_e32 v95, 0xffff0000, v53
	global_load_dwordx4 v[54:57], v[98:99], off
	global_load_dwordx4 v[50:53], v[96:97], off
	v_pk_mul_f32 v[96:97], v[22:23], v[66:67]
	v_pk_mul_f32 v[98:99], v[24:25], v[62:63]
	v_pk_fma_f32 v[86:87], v[18:19], v[86:87], v[96:97]
	v_pk_fma_f32 v[70:71], v[20:21], v[70:71], v[98:99]
	v_pk_fma_f32 v[86:87], v[14:15], v[80:81], v[86:87]
	v_pk_fma_f32 v[70:71], v[16:17], v[82:83], v[70:71]
	v_pk_mul_f32 v[58:59], v[86:87], v[58:59]
	v_pk_mul_f32 v[60:61], v[70:71], v[60:61]
	v_pk_mul_f32 v[70:71], v[10:11], v[68:69]
	v_pk_mul_f32 v[86:87], v[12:13], v[64:65]
	s_or_b32 s18, s30, 25
	v_pk_fma_f32 v[72:73], v[8:9], v[72:73], v[86:87]
	v_pk_fma_f32 v[70:71], v[6:7], v[88:89], v[70:71]
	s_ashr_i32 s19, s18, 31
	v_pk_fma_f32 v[70:71], v[2:3], v[84:85], v[70:71]
	v_pk_fma_f32 v[72:73], v[4:5], v[90:91], v[72:73]
	v_pk_mul_f32 v[70:71], v[70:71], v[92:93]
	v_pk_mul_f32 v[72:73], v[72:73], v[94:95]
	s_lshl_b64 s[18:19], s[18:19], 11
	v_pk_mul_f32 v[98:99], v[24:25], v[82:83]
	v_cvt_pk_bf16_f32 v58, v58, v59
	v_cvt_pk_bf16_f32 v59, v60, v61
	v_cvt_pk_bf16_f32 v60, v70, v71
	v_cvt_pk_bf16_f32 v61, v72, v73
	v_lshl_add_u64 v[70:71], v[76:77], 0, s[18:19]
	s_waitcnt vmcnt(10)
; __device__ __forceinline__ u32x4 pack8(const f32x4 a, const f32x4 b) { u32x4 w; w.x = cvt_pk_bf16(a[0], a[1]); w.y = cvt_pk_bf16(a[2], a[3]); w.z = cvt_pk_bf16(b[0], b[1]); w.w = cvt_pk_bf16(b[2], b[3]); return w; }
; __device__ __forceinline__ void p5_conv(const Args& A, int lane, int wave, bf16_t* Gout) {
;     ...
;         for (int t = 0; t < 32; ++t) { const size_t off = (size_t)(r0 + t) * DM + c0;
;             f32x4 ca, cb, ba, bb; pg8::unpack8(cq[t & 3], ca, cb); pg8::unpack8(bq[t & 3], ba, bb);
;             if (t + 4 < 32) { const size_t offn = (size_t)(r0 + t + 4) * DM + c0; cq[t & 3] = *(const u32x4*)(CU + offn); bq[t & 3] = *(const u32x4*)(BG + offn); }
;             const f32x4 oa = ba * ((w0a * p2a + w1a * p1a) + w2a * ca), ob = bb * ((w0b * p2b + w1b * p1b) + w2b * cb);
;             *(u32x4*)(Gout + off) = pg8::pack8(oa, ob);
;             p2a = p1a; p2b = p1b; p1a = ca; p1b = cb; }
	v_lshlrev_b32_e32 v72, 16, v47
	v_and_b32_e32 v73, 0xffff0000, v47
	v_pk_fma_f32 v[62:63], v[20:21], v[62:63], v[98:99]
	global_store_dwordx4 v[70:71], v[58:61], off
	s_or_b32 s18, s30, 30
	v_pk_fma_f32 v[62:63], v[16:17], v[72:73], v[62:63]
	s_waitcnt vmcnt(10)
	v_lshlrev_b32_e32 v60, 16, v35
	v_and_b32_e32 v61, 0xffff0000, v35
	s_ashr_i32 s19, s18, 31
	v_pk_mul_f32 v[96:97], v[22:23], v[80:81]
	v_pk_mul_f32 v[60:61], v[62:63], v[60:61]
	v_pk_mul_f32 v[62:63], v[10:11], v[84:85]
	s_or_b32 s20, s30, 26
	v_lshlrev_b32_e32 v70, 16, v46
	v_and_b32_e32 v71, 0xffff0000, v46
	v_lshlrev_b32_e32 v86, 16, v48
	v_and_b32_e32 v87, 0xffff0000, v48
	s_lshl_b64 s[18:19], s[18:19], 11
	v_pk_fma_f32 v[66:67], v[18:19], v[66:67], v[96:97]
	v_pk_fma_f32 v[62:63], v[6:7], v[68:69], v[62:63]
	s_ashr_i32 s21, s20, 31
	v_lshlrev_b32_e32 v58, 16, v34
	v_and_b32_e32 v59, 0xffff0000, v34
	v_lshlrev_b32_e32 v92, 16, v36
	v_and_b32_e32 v93, 0xffff0000, v36
	v_or_b32_e32 v34, s18, v74
	v_mov_b32_e32 v35, s19
	v_pk_fma_f32 v[66:67], v[14:15], v[70:71], v[66:67]
	v_pk_fma_f32 v[62:63], v[2:3], v[86:87], v[62:63]
	v_lshlrev_b32_e32 v94, 16, v37
	v_and_b32_e32 v95, 0xffff0000, v37
	v_lshl_add_u64 v[36:37], s[4:5], 0, v[34:35]
	v_lshl_add_u64 v[34:35], s[6:7], 0, v[34:35]
	v_pk_mul_f32 v[58:59], v[66:67], v[58:59]
	v_pk_mul_f32 v[66:67], v[12:13], v[90:91]
	v_pk_mul_f32 v[62:63], v[62:63], v[92:93]
	s_lshl_b64 s[20:21], s[20:21], 11
	v_lshlrev_b32_e32 v88, 16, v49
	v_and_b32_e32 v89, 0xffff0000, v49
	global_load_dwordx4 v[46:49], v[34:35], off
	s_nop 0
	global_load_dwordx4 v[34:37], v[36:37], off
	v_pk_fma_f32 v[64:65], v[8:9], v[64:65], v[66:67]
	v_cvt_pk_bf16_f32 v58, v58, v59
	v_cvt_pk_bf16_f32 v59, v60, v61
	v_cvt_pk_bf16_f32 v60, v62, v63
	v_lshl_add_u64 v[62:63], v[76:77], 0, s[20:21]
	s_or_b32 s20, s30, 31
	v_pk_fma_f32 v[64:65], v[4:5], v[88:89], v[64:65]
	s_ashr_i32 s21, s20, 31
	v_pk_mul_f32 v[64:65], v[64:65], v[94:95]
	s_lshl_b64 s[20:21], s[20:21], 11
	v_cvt_pk_bf16_f32 v61, v64, v65
	global_store_dwordx4 v[62:63], v[58:61], off
	s_waitcnt vmcnt(11)
	v_lshlrev_b32_e32 v62, 16, v38
	v_and_b32_e32 v63, 0xffff0000, v38
	s_waitcnt vmcnt(10)
	v_lshlrev_b32_e32 v58, 16, v26
	v_and_b32_e32 v59, 0xffff0000, v26
	v_lshlrev_b32_e32 v60, 16, v27
	v_and_b32_e32 v61, 0xffff0000, v27
	v_or_b32_e32 v26, s20, v74
	v_mov_b32_e32 v27, s21
	v_lshlrev_b32_e32 v64, 16, v39
	v_and_b32_e32 v65, 0xffff0000, v39
	v_lshl_add_u64 v[38:39], s[4:5], 0, v[26:27]
	v_lshl_add_u64 v[26:27], s[6:7], 0, v[26:27]
	v_lshlrev_b32_e32 v66, 16, v40
	v_and_b32_e32 v67, 0xffff0000, v40
	v_lshlrev_b32_e32 v68, 16, v41
	v_and_b32_e32 v69, 0xffff0000, v41
	v_lshlrev_b32_e32 v92, 16, v28
	v_and_b32_e32 v93, 0xffff0000, v28
	v_lshlrev_b32_e32 v94, 16, v29
	v_and_b32_e32 v95, 0xffff0000, v29
	global_load_dwordx4 v[26:29], v[26:27], off
	s_nop 0
	global_load_dwordx4 v[38:41], v[38:39], off
	v_pk_mul_f32 v[96:97], v[22:23], v[70:71]
	v_pk_mul_f32 v[98:99], v[24:25], v[72:73]
	v_pk_fma_f32 v[80:81], v[18:19], v[80:81], v[96:97]
	v_pk_fma_f32 v[82:83], v[20:21], v[82:83], v[98:99]
	v_pk_fma_f32 v[80:81], v[14:15], v[62:63], v[80:81]
	s_or_b32 s22, s30, 27
	v_pk_mul_f32 v[58:59], v[80:81], v[58:59]
	v_pk_mul_f32 v[80:81], v[10:11], v[86:87]
	v_pk_fma_f32 v[82:83], v[16:17], v[64:65], v[82:83]
	v_pk_fma_f32 v[80:81], v[6:7], v[84:85], v[80:81]
	s_ashr_i32 s23, s22, 31
	v_pk_mul_f32 v[60:61], v[82:83], v[60:61]
	v_pk_mul_f32 v[82:83], v[12:13], v[88:89]
	v_pk_fma_f32 v[80:81], v[2:3], v[66:67], v[80:81]
	v_pk_fma_f32 v[82:83], v[8:9], v[90:91], v[82:83]
	v_pk_mul_f32 v[80:81], v[80:81], v[92:93]
	s_lshl_b64 s[22:23], s[22:23], 11
	v_pk_fma_f32 v[82:83], v[4:5], v[68:69], v[82:83]
	v_cvt_pk_bf16_f32 v58, v58, v59
	v_cvt_pk_bf16_f32 v59, v60, v61
	v_cvt_pk_bf16_f32 v60, v80, v81
	v_lshl_add_u64 v[80:81], v[76:77], 0, s[22:23]
	v_pk_mul_f32 v[84:85], v[22:23], v[62:63]
	v_pk_mul_f32 v[90:91], v[24:25], v[64:65]
	v_pk_mul_f32 v[82:83], v[82:83], v[94:95]
	v_pk_fma_f32 v[72:73], v[20:21], v[72:73], v[90:91]
	v_cvt_pk_bf16_f32 v61, v82, v83
	global_store_dwordx4 v[80:81], v[58:61], off
	v_pk_fma_f32 v[70:71], v[18:19], v[70:71], v[84:85]
	s_waitcnt vmcnt(10)
	v_lshlrev_b32_e32 v82, 16, v30
	v_lshlrev_b32_e32 v58, 16, v42
	v_and_b32_e32 v59, 0xffff0000, v42
	v_lshlrev_b32_e32 v42, 16, v43
	v_and_b32_e32 v43, 0xffff0000, v43
	v_and_b32_e32 v83, 0xffff0000, v30
	v_lshlrev_b32_e32 v30, 16, v31
	v_and_b32_e32 v31, 0xffff0000, v31
	v_pk_fma_f32 v[70:71], v[14:15], v[58:59], v[70:71]
	v_pk_fma_f32 v[72:73], v[16:17], v[42:43], v[72:73]
	v_lshlrev_b32_e32 v60, 16, v44
	v_pk_mul_f32 v[72:73], v[72:73], v[30:31]
	v_pk_mul_f32 v[30:31], v[70:71], v[82:83]
	v_pk_mul_f32 v[70:71], v[10:11], v[66:67]
	v_pk_mul_f32 v[82:83], v[12:13], v[68:69]
	v_and_b32_e32 v61, 0xffff0000, v44
	v_lshlrev_b32_e32 v44, 16, v45
	v_and_b32_e32 v45, 0xffff0000, v45
	v_pk_fma_f32 v[82:83], v[8:9], v[88:89], v[82:83]
	v_pk_fma_f32 v[70:71], v[6:7], v[86:87], v[70:71]
	v_lshlrev_b32_e32 v80, 16, v32
	v_and_b32_e32 v81, 0xffff0000, v32
	v_lshlrev_b32_e32 v32, 16, v33
	v_and_b32_e32 v33, 0xffff0000, v33
	v_pk_fma_f32 v[70:71], v[2:3], v[60:61], v[70:71]
	v_pk_fma_f32 v[82:83], v[4:5], v[44:45], v[82:83]
	v_cvt_pk_bf16_f32 v30, v30, v31
	v_cvt_pk_bf16_f32 v31, v72, v73
	s_waitcnt vmcnt(8)
	v_lshlrev_b32_e32 v72, 16, v56
	v_pk_mul_f32 v[82:83], v[82:83], v[32:33]
	v_pk_mul_f32 v[32:33], v[70:71], v[80:81]
	v_lshl_add_u64 v[70:71], v[76:77], 0, s[14:15]
	v_cvt_pk_bf16_f32 v32, v32, v33
	v_cvt_pk_bf16_f32 v33, v82, v83
	v_pk_mul_f32 v[80:81], v[22:23], v[58:59]
	v_pk_mul_f32 v[82:83], v[24:25], v[42:43]
	global_store_dwordx4 v[70:71], v[30:33], off
	v_lshlrev_b32_e32 v70, 16, v54
	v_and_b32_e32 v71, 0xffff0000, v54
	v_lshlrev_b32_e32 v54, 16, v55
	v_and_b32_e32 v55, 0xffff0000, v55
	v_pk_fma_f32 v[64:65], v[20:21], v[64:65], v[82:83]
	v_pk_fma_f32 v[62:63], v[18:19], v[62:63], v[80:81]
	s_waitcnt vmcnt(8)
; __device__ __forceinline__ u32x4 pack8(const f32x4 a, const f32x4 b) { u32x4 w; w.x = cvt_pk_bf16(a[0], a[1]); w.y = cvt_pk_bf16(a[2], a[3]); w.z = cvt_pk_bf16(b[0], b[1]); w.w = cvt_pk_bf16(b[2], b[3]); return w; }
; __device__ __forceinline__ void p5_conv(const Args& A, int lane, int wave, bf16_t* Gout) {
;     ...
;     for (int wi = gw; wi < (M / 32) * 2; wi += NGW) {
;         const int r0 = (wi >> 1) * 32, c0 = (wi & 1) * 512 + lane * 8;
;         const f32x4 w0a = *(const f32x4*)(A.conv_w + c0), w0b = *(const f32x4*)(A.conv_w + c0 + 4), w1a = *(const f32x4*)(A.conv_w + DM + c0), w1b = *(const f32x4*)(A.conv_w + DM + c0 + 4),
;                     w2a = *(const f32x4*)(A.conv_w + 2 * DM + c0), w2b = *(const f32x4*)(A.conv_w + 2 * DM + c0 + 4);
;         f32x4 p2a = {0.f, 0.f, 0.f, 0.f}, p2b = p2a, p1a = p2a, p1b = p2a;
;         if ((r0 & (SEQ - 1)) != 0) { pg8::unpack8(*(const u32x4*)(CU + (size_t)(r0 - 2) * DM + c0), p2a, p2b); pg8::unpack8(*(const u32x4*)(CU + (size_t)(r0 - 1) * DM + c0), p1a, p1b); }
;         u32x4 cq[4], bq[4];
; #pragma unroll
;         for (int i = 0; i < 4; ++i) { const size_t off = (size_t)(r0 + i) * DM + c0; cq[i] = *(const u32x4*)(CU + off); bq[i] = *(const u32x4*)(BG + off); }
; #pragma unroll
;         for (int t = 0; t < 32; ++t) { const size_t off = (size_t)(r0 + t) * DM + c0;
;             f32x4 ca, cb, ba, bb; pg8::unpack8(cq[t & 3], ca, cb); pg8::unpack8(bq[t & 3], ba, bb);
;             if (t + 4 < 32) { const size_t offn = (size_t)(r0 + t + 4) * DM + c0; cq[t & 3] = *(const u32x4*)(CU + offn); bq[t & 3] = *(const u32x4*)(BG + offn); }
;             const f32x4 oa = ba * ((w0a * p2a + w1a * p1a) + w2a * ca), ob = bb * ((w0b * p2b + w1b * p1b) + w2b * cb);
;             *(u32x4*)(Gout + off) = pg8::pack8(oa, ob);
;             p2a = p1a; p2b = p1b; p1a = ca; p1b = cb; }
	v_lshlrev_b32_e32 v30, 16, v52
	v_and_b32_e32 v31, 0xffff0000, v52
	v_lshlrev_b32_e32 v32, 16, v53
	v_and_b32_e32 v33, 0xffff0000, v53
	v_lshlrev_b32_e32 v52, 16, v50
	v_and_b32_e32 v53, 0xffff0000, v50
	v_lshlrev_b32_e32 v50, 16, v51
	v_and_b32_e32 v51, 0xffff0000, v51
	v_pk_fma_f32 v[62:63], v[14:15], v[70:71], v[62:63]
	v_pk_fma_f32 v[64:65], v[16:17], v[54:55], v[64:65]
	v_pk_mul_f32 v[52:53], v[62:63], v[52:53]
	v_pk_mul_f32 v[50:51], v[64:65], v[50:51]
	v_pk_mul_f32 v[62:63], v[10:11], v[60:61]
	v_pk_mul_f32 v[64:65], v[12:13], v[44:45]
	v_and_b32_e32 v73, 0xffff0000, v56
	v_lshlrev_b32_e32 v56, 16, v57
	v_and_b32_e32 v57, 0xffff0000, v57
	v_pk_fma_f32 v[64:65], v[8:9], v[68:69], v[64:65]
	v_pk_fma_f32 v[62:63], v[6:7], v[66:67], v[62:63]
	v_pk_fma_f32 v[64:65], v[4:5], v[56:57], v[64:65]
	v_pk_fma_f32 v[62:63], v[2:3], v[72:73], v[62:63]
	v_pk_mul_f32 v[64:65], v[64:65], v[32:33]
	v_pk_mul_f32 v[32:33], v[62:63], v[30:31]
	v_cvt_pk_bf16_f32 v30, v52, v53
	v_cvt_pk_bf16_f32 v31, v50, v51
	v_lshl_add_u64 v[50:51], v[76:77], 0, s[16:17]
	v_cvt_pk_bf16_f32 v32, v32, v33
	v_cvt_pk_bf16_f32 v33, v64, v65
	v_pk_mul_f32 v[62:63], v[22:23], v[70:71]
	v_pk_mul_f32 v[64:65], v[24:25], v[54:55]
	global_store_dwordx4 v[50:51], v[30:33], off
	s_waitcnt vmcnt(7)
	v_lshlrev_b32_e32 v50, 16, v46
	v_and_b32_e32 v51, 0xffff0000, v46
	v_lshlrev_b32_e32 v46, 16, v47
	v_and_b32_e32 v47, 0xffff0000, v47
	v_pk_fma_f32 v[42:43], v[20:21], v[42:43], v[64:65]
	v_pk_fma_f32 v[58:59], v[18:19], v[58:59], v[62:63]
	s_waitcnt vmcnt(6)
	v_lshlrev_b32_e32 v30, 16, v36
	v_and_b32_e32 v31, 0xffff0000, v36
	v_lshlrev_b32_e32 v32, 16, v37
	v_and_b32_e32 v33, 0xffff0000, v37
	v_lshlrev_b32_e32 v36, 16, v34
	v_and_b32_e32 v37, 0xffff0000, v34
	v_lshlrev_b32_e32 v34, 16, v35
	v_and_b32_e32 v35, 0xffff0000, v35
	v_pk_fma_f32 v[58:59], v[14:15], v[50:51], v[58:59]
	v_pk_fma_f32 v[42:43], v[16:17], v[46:47], v[42:43]
	v_pk_mul_f32 v[36:37], v[58:59], v[36:37]
	v_pk_mul_f32 v[34:35], v[42:43], v[34:35]
	v_pk_mul_f32 v[42:43], v[10:11], v[72:73]
	v_pk_mul_f32 v[58:59], v[12:13], v[56:57]
	v_lshlrev_b32_e32 v52, 16, v48
	v_and_b32_e32 v53, 0xffff0000, v48
	v_lshlrev_b32_e32 v48, 16, v49
	v_and_b32_e32 v49, 0xffff0000, v49
	v_pk_fma_f32 v[44:45], v[8:9], v[44:45], v[58:59]
	v_pk_fma_f32 v[42:43], v[6:7], v[60:61], v[42:43]
	v_pk_fma_f32 v[44:45], v[4:5], v[48:49], v[44:45]
	v_pk_fma_f32 v[42:43], v[2:3], v[52:53], v[42:43]
	v_pk_mul_f32 v[44:45], v[44:45], v[32:33]
	v_pk_mul_f32 v[32:33], v[42:43], v[30:31]
	v_cvt_pk_bf16_f32 v30, v36, v37
	v_cvt_pk_bf16_f32 v31, v34, v35
	v_lshl_add_u64 v[34:35], v[76:77], 0, s[18:19]
	v_pk_mul_f32 v[10:11], v[10:11], v[52:53]
	v_pk_mul_f32 v[12:13], v[12:13], v[48:49]
	v_cvt_pk_bf16_f32 v32, v32, v33
	v_cvt_pk_bf16_f32 v33, v44, v45
	global_store_dwordx4 v[34:35], v[30:33], off
	s_waitcnt vmcnt(4)
	v_lshlrev_b32_e32 v34, 16, v38
	v_and_b32_e32 v35, 0xffff0000, v38
	v_lshlrev_b32_e32 v36, 16, v39
	v_and_b32_e32 v37, 0xffff0000, v39
	v_lshlrev_b32_e32 v38, 16, v28
	v_and_b32_e32 v39, 0xffff0000, v28
	v_lshlrev_b32_e32 v28, 16, v29
	v_and_b32_e32 v29, 0xffff0000, v29
	v_pk_mul_f32 v[22:23], v[22:23], v[50:51]
	v_pk_mul_f32 v[24:25], v[24:25], v[46:47]
	v_pk_fma_f32 v[8:9], v[8:9], v[56:57], v[12:13]
	v_pk_fma_f32 v[6:7], v[6:7], v[72:73], v[10:11]
	v_lshlrev_b32_e32 v30, 16, v40
	v_and_b32_e32 v31, 0xffff0000, v40
	v_lshlrev_b32_e32 v32, 16, v41
	v_and_b32_e32 v33, 0xffff0000, v41
	v_lshlrev_b32_e32 v40, 16, v26
	v_and_b32_e32 v41, 0xffff0000, v26
	v_lshlrev_b32_e32 v26, 16, v27
	v_and_b32_e32 v27, 0xffff0000, v27
	v_pk_fma_f32 v[20:21], v[20:21], v[54:55], v[24:25]
	v_pk_fma_f32 v[18:19], v[18:19], v[70:71], v[22:23]
	v_pk_fma_f32 v[2:3], v[2:3], v[38:39], v[6:7]
	v_pk_fma_f32 v[4:5], v[4:5], v[28:29], v[8:9]
	v_pk_fma_f32 v[14:15], v[14:15], v[40:41], v[18:19]
	v_pk_fma_f32 v[16:17], v[16:17], v[26:27], v[20:21]
	v_pk_mul_f32 v[6:7], v[4:5], v[32:33]
	v_pk_mul_f32 v[4:5], v[2:3], v[30:31]
	s_add_i32 s26, s26, s27
	s_add_i32 s28, s28, s29
	s_add_i32 s30, s30, s31
	v_pk_mul_f32 v[16:17], v[16:17], v[36:37]
	v_pk_mul_f32 v[14:15], v[14:15], v[34:35]
	s_cmpk_lt_i32 s26, 0x800
	v_cvt_pk_bf16_f32 v2, v14, v15
	v_cvt_pk_bf16_f32 v3, v16, v17
	v_cvt_pk_bf16_f32 v4, v4, v5
	v_cvt_pk_bf16_f32 v5, v6, v7
	v_lshl_add_u64 v[6:7], v[76:77], 0, s[20:21]
	global_store_dwordx4 v[6:7], v[2:5], off
	s_cbranch_scc0 .LBB0_634
.LBB0_632:
	s_and_b32 s14, s28, 0x200
	v_or_b32_e32 v26, s14, v1
	v_lshlrev_b32_e32 v27, 2, v26
	global_load_dwordx4 v[6:9], v27, s[2:3] offset:16
	global_load_dwordx4 v[18:21], v27, s[2:3]
	global_load_dwordx4 v[10:13], v27, s[8:9] offset:16
	global_load_dwordx4 v[22:25], v27, s[8:9]
	global_load_dwordx4 v[2:5], v27, s[10:11] offset:16
	global_load_dwordx4 v[14:17], v27, s[10:11]
	s_and_b32 s14, s30, 0xffffffe0
	v_lshlrev_b32_e32 v74, 1, v26
	s_ashr_i32 s15, s14, 31
	s_lshl_b64 s[18:19], s[14:15], 11
	v_or_b32_e32 v46, s18, v74
	v_mov_b32_e32 v47, s19
	v_lshl_add_u64 v[42:43], s[6:7], 0, v[46:47]
	global_load_dwordx4 v[42:45], v[42:43], off
	v_lshl_add_u64 v[46:47], s[4:5], 0, v[46:47]
	s_or_b32 s16, s14, 1
	global_load_dwordx4 v[46:49], v[46:47], off
	s_ashr_i32 s17, s16, 31
	s_lshl_b64 s[20:21], s[16:17], 11
	v_or_b32_e32 v54, s20, v74
	v_mov_b32_e32 v55, s21
	v_lshl_add_u64 v[50:51], s[6:7], 0, v[54:55]
	v_lshl_add_u64 v[54:55], s[4:5], 0, v[54:55]
	global_load_dwordx4 v[50:53], v[50:51], off
	global_load_dwordx4 v[58:61], v[54:55], off
	s_and_b32 s15, s26, 0x1fe
	s_cmp_eq_u32 s15, 0
	v_mov_b32_e32 v26, 0
	v_mov_b32_e32 v27, 0
	v_mov_b32_e32 v28, 0
	v_mov_b32_e32 v29, 0
	v_mov_b32_e32 v38, 0
	v_mov_b32_e32 v39, 0
	v_mov_b32_e32 v40, 0
	v_mov_b32_e32 v41, 0
	v_mov_b32_e32 v30, 0
	v_mov_b32_e32 v31, 0
	v_mov_b32_e32 v32, 0
	v_mov_b32_e32 v33, 0
	v_mov_b32_e32 v34, 0
	v_mov_b32_e32 v35, 0
	v_mov_b32_e32 v36, 0
	v_mov_b32_e32 v37, 0
	s_cbranch_scc1 .LBB0_631
	s_ashr_i32 s15, s14, 31
	s_lshl_b64 s[16:17], s[14:15], 11
	s_add_u32 s16, s6, s16
	s_addc_u32 s17, s7, s17
	global_load_dwordx4 v[26:29], v74, s[16:17] offset:-4096
	global_load_dwordx4 v[30:33], v74, s[16:17] offset:-2048
	s_waitcnt vmcnt(0)
	v_lshlrev_b32_e32 v38, 16, v26
	v_and_b32_e32 v39, 0xffff0000, v26
	v_lshlrev_b32_e32 v40, 16, v27
	v_and_b32_e32 v41, 0xffff0000, v27
	v_lshlrev_b32_e32 v26, 16, v28
	v_and_b32_e32 v27, 0xffff0000, v28
	v_lshlrev_b32_e32 v28, 16, v29
	v_and_b32_e32 v29, 0xffff0000, v29
	v_lshlrev_b32_e32 v34, 16, v30
	v_and_b32_e32 v35, 0xffff0000, v30
	v_lshlrev_b32_e32 v36, 16, v31
	v_and_b32_e32 v37, 0xffff0000, v31
	v_lshlrev_b32_e32 v30, 16, v32
	v_and_b32_e32 v31, 0xffff0000, v32
	v_lshlrev_b32_e32 v32, 16, v33
	v_and_b32_e32 v33, 0xffff0000, v33
	s_branch .LBB0_631
